# nt hint on the streaming stores of the conv+GeGLU pass (ACT) and of the final residual pass (out), on top of v9
# speedup vs baseline: 1.0053x; 1.0042x over previous
.LBB0_859:
	v_mov_b32_e32 v130, v1
	v_add_u32_e32 v1, s14, v130
	v_add_u32_e32 v158, s2, v135
	v_cmp_eq_u32_sdwa s[0:1], v130, v159 src0_sel:BYTE_0 src1_sel:DWORD
	v_add_u32_e32 v131, -7, v158
	v_add_u32_e32 v218, -7, v135
	v_cndmask_b32_e64 v160, 1.0, 0, s[0:1]
	v_cmp_gt_i32_e64 s[0:1], s16, v1
	s_waitcnt vmcnt(16)
	v_cmp_lt_i32_e32 vcc, s3, v1
	v_lshlrev_b32_e32 v178, 16, v81
	v_cndmask_b32_e64 v175, v218, v131, s[0:1]
	v_and_b32_e32 v130, 0x7f8, v175
	v_cmp_ne_u32_e64 s[0:1], 0, v130
	v_add_u32_e32 v130, -2, v175
	v_and_b32_e32 v179, 0xffff0000, v81
	v_cndmask_b32_e64 v130, v175, v130, s[0:1]
	v_subbrev_co_u32_e64 v131, s[0:1], 0, v175, s[0:1]
	v_mad_i64_i32 v[162:163], s[0:1], v130, s15, v[152:153]
	v_mad_i64_i32 v[164:165], s[0:1], v131, s15, v[152:153]
	v_lshlrev_b32_e32 v130, 16, v65
	v_and_b32_e32 v131, 0xffff0000, v65
	v_pk_mul_f32 v[194:195], v[160:161], v[130:131] op_sel_hi:[0,1]
	v_pk_mul_f32 v[130:131], v[160:161], v[178:179] op_sel_hi:[0,1]
	v_lshlrev_b32_e32 v178, 16, v64
	v_and_b32_e32 v179, 0xffff0000, v64
	v_lshlrev_b32_e32 v132, 16, v61
	v_and_b32_e32 v133, 0xffff0000, v61
	v_lshlrev_b32_e32 v176, 16, v77
	v_and_b32_e32 v177, 0xffff0000, v77
	v_lshlrev_b32_e32 v64, 16, v60
	v_and_b32_e32 v65, 0xffff0000, v60
	v_lshlrev_b32_e32 v60, 16, v76
	v_and_b32_e32 v61, 0xffff0000, v76
	v_lshlrev_b32_e32 v76, 16, v80
	v_and_b32_e32 v77, 0xffff0000, v80
	v_pk_mul_f32 v[80:81], v[160:161], v[178:179] op_sel_hi:[0,1]
	v_pk_mul_f32 v[196:197], v[160:161], v[64:65] op_sel_hi:[0,1]
	v_pk_mul_f32 v[60:61], v[160:161], v[60:61] op_sel_hi:[0,1]
	v_pk_fma_f32 v[64:65], v[2:3], v[80:81], v[42:43]
	v_pk_mul_f32 v[198:199], v[160:161], v[76:77] op_sel_hi:[0,1]
	v_pk_fma_f32 v[200:201], v[10:11], v[196:197], v[64:65]
	v_pk_fma_f32 v[64:65], v[148:149], v[60:61], v[142:143]
	v_lshlrev_b32_e32 v76, 16, v59
	v_pk_fma_f32 v[202:203], v[22:23], v[198:199], v[64:65]
	v_lshlrev_b32_e32 v64, 16, v63
	v_and_b32_e32 v65, 0xffff0000, v63
	v_and_b32_e32 v77, 0xffff0000, v59
	v_lshlrev_b32_e32 v178, 16, v75
	v_and_b32_e32 v179, 0xffff0000, v75
	v_pk_mul_f32 v[64:65], v[160:161], v[64:65] op_sel_hi:[0,1]
	v_lshlrev_b32_e32 v180, 16, v79
	v_and_b32_e32 v181, 0xffff0000, v79
	v_pk_mul_f32 v[204:205], v[160:161], v[76:77] op_sel_hi:[0,1]
	v_pk_mul_f32 v[76:77], v[160:161], v[178:179] op_sel_hi:[0,1]
	v_pk_fma_f32 v[178:179], v[8:9], v[64:65], v[48:49]
	v_pk_mul_f32 v[206:207], v[160:161], v[180:181] op_sel_hi:[0,1]
	v_pk_fma_f32 v[208:209], v[16:17], v[204:205], v[178:179]
	v_pk_fma_f32 v[178:179], v[146:147], v[76:77], v[140:141]
	v_and_b32_e32 v63, 0xffff0000, v58
	v_pk_fma_f32 v[210:211], v[20:21], v[206:207], v[178:179]
	v_lshlrev_b32_e32 v178, 16, v62
	v_and_b32_e32 v179, 0xffff0000, v62
	v_lshlrev_b32_e32 v62, 16, v58
	v_lshlrev_b32_e32 v58, 16, v74
	v_and_b32_e32 v59, 0xffff0000, v74
	v_lshlrev_b32_e32 v74, 16, v78
	v_and_b32_e32 v75, 0xffff0000, v78
	v_pk_mul_f32 v[78:79], v[160:161], v[178:179] op_sel_hi:[0,1]
	v_pk_mul_f32 v[132:133], v[160:161], v[132:133] op_sel_hi:[0,1]
	v_pk_mul_f32 v[212:213], v[160:161], v[62:63] op_sel_hi:[0,1]
	v_pk_mul_f32 v[58:59], v[160:161], v[58:59] op_sel_hi:[0,1]
	v_pk_fma_f32 v[62:63], v[6:7], v[78:79], v[46:47]
	v_pk_mul_f32 v[176:177], v[160:161], v[176:177] op_sel_hi:[0,1]
	v_pk_mul_f32 v[214:215], v[160:161], v[74:75] op_sel_hi:[0,1]
	v_pk_fma_f32 v[160:161], v[14:15], v[212:213], v[62:63]
	v_pk_fma_f32 v[62:63], v[138:139], v[58:59], v[136:137]
	v_lshl_add_u64 v[166:167], v[162:163], 0, s[8:9]
	v_pk_fma_f32 v[216:217], v[18:19], v[214:215], v[62:63]
	global_load_dwordx4 v[62:65], v[162:163], off nt
	global_load_dwordx4 v[58:61], v[164:165], off nt
	global_load_dwordx4 v[74:77], v[166:167], off nt
	v_lshl_add_u64 v[168:169], v[164:165], 0, s[8:9]
	global_load_dwordx4 v[78:81], v[168:169], off nt
	s_waitcnt vmcnt(18)
	v_mad_i64_i32 v[170:171], s[0:1], v175, s15, v[152:153]
	v_lshlrev_b32_e32 v192, 16, v66
	v_and_b32_e32 v193, 0xffff0000, v66
	v_pk_fma_f32 v[160:161], v[30:31], v[192:193], v[160:161]
	v_lshlrev_b32_e32 v188, 16, v67
	v_mul_f32_e32 v162, 0x3d372713, v160
	v_mul_f32_e32 v163, 0x3d372713, v161
	v_mul_f32_e32 v162, v160, v162
	v_mul_f32_e32 v163, v161, v163
	v_fma_f32 v162, v160, v162, v160
	v_fma_f32 v163, v161, v163, v161
	v_mul_f32_e32 v162, 0xbfcc422a, v162
	v_mul_f32_e32 v163, 0xbfcc422a, v163
	v_mul_f32_e32 v162, 0x3fb8aa3b, v162
	v_mul_f32_e32 v163, 0x3fb8aa3b, v163
	v_exp_f32_e32 v162, v162
	v_exp_f32_e32 v163, v163
	v_and_b32_e32 v189, 0xffff0000, v67
	v_lshlrev_b32_e32 v190, 16, v50
	v_add_f32_e32 v162, 1.0, v162
	v_add_f32_e32 v163, 1.0, v163
	v_rcp_f32_e32 v162, v162
	v_rcp_f32_e32 v163, v163
	v_and_b32_e32 v191, 0xffff0000, v50
	v_pk_fma_f32 v[164:165], v[34:35], v[190:191], v[216:217]
	v_lshlrev_b32_e32 v184, 16, v68
	v_pk_mul_f32 v[160:161], v[160:161], v[162:163]
	v_pk_fma_f32 v[162:163], v[32:33], v[188:189], v[208:209]
	v_pk_mul_f32 v[160:161], v[164:165], v[160:161]
	v_mul_f32_e32 v164, 0x3d372713, v162
	v_mul_f32_e32 v165, 0x3d372713, v163
	v_mul_f32_e32 v164, v162, v164
	v_mul_f32_e32 v165, v163, v165
	v_fma_f32 v164, v162, v164, v162
	v_fma_f32 v165, v163, v165, v163
	v_mul_f32_e32 v164, 0xbfcc422a, v164
	v_mul_f32_e32 v165, 0xbfcc422a, v165
	v_mul_f32_e32 v164, 0x3fb8aa3b, v164
	v_mul_f32_e32 v165, 0x3fb8aa3b, v165
	v_exp_f32_e32 v164, v164
	v_exp_f32_e32 v165, v165
	v_and_b32_e32 v185, 0xffff0000, v68
	v_lshlrev_b32_e32 v186, 16, v51
	v_add_f32_e32 v164, 1.0, v164
	v_add_f32_e32 v165, 1.0, v165
	v_rcp_f32_e32 v164, v164
	v_rcp_f32_e32 v165, v165
	v_and_b32_e32 v187, 0xffff0000, v51
	v_pk_fma_f32 v[166:167], v[36:37], v[186:187], v[210:211]
	v_lshlrev_b32_e32 v180, 16, v69
	v_pk_mul_f32 v[162:163], v[162:163], v[164:165]
	v_pk_fma_f32 v[164:165], v[26:27], v[184:185], v[200:201]
	v_pk_mul_f32 v[162:163], v[166:167], v[162:163]
	v_mul_f32_e32 v166, 0x3d372713, v164
	v_mul_f32_e32 v167, 0x3d372713, v165
	v_mul_f32_e32 v166, v164, v166
	v_mul_f32_e32 v167, v165, v167
	v_fma_f32 v166, v164, v166, v164
	v_fma_f32 v167, v165, v167, v165
	v_mul_f32_e32 v166, 0xbfcc422a, v166
	v_mul_f32_e32 v167, 0xbfcc422a, v167
	v_mul_f32_e32 v166, 0x3fb8aa3b, v166
	v_mul_f32_e32 v167, 0x3fb8aa3b, v167
	v_exp_f32_e32 v166, v166
	v_exp_f32_e32 v167, v167
	v_and_b32_e32 v181, 0xffff0000, v69
	v_lshlrev_b32_e32 v182, 16, v52
	v_add_f32_e32 v166, 1.0, v166
	v_add_f32_e32 v167, 1.0, v167
	v_rcp_f32_e32 v166, v166
	v_rcp_f32_e32 v167, v167
	v_and_b32_e32 v183, 0xffff0000, v52
	v_pk_fma_f32 v[168:169], v[38:39], v[182:183], v[202:203]
	v_lshlrev_b32_e32 v178, 16, v53
	v_pk_mul_f32 v[164:165], v[164:165], v[166:167]
	v_pk_fma_f32 v[166:167], v[4:5], v[194:195], v[44:45]
	v_pk_mul_f32 v[164:165], v[168:169], v[164:165]
	v_pk_fma_f32 v[166:167], v[12:13], v[132:133], v[166:167]
	v_and_b32_e32 v179, 0xffff0000, v53
	v_pk_fma_f32 v[166:167], v[28:29], v[180:181], v[166:167]
	v_lshl_add_u64 v[172:173], v[170:171], 0, s[8:9]
	v_mul_f32_e32 v168, 0x3d372713, v166
	v_mul_f32_e32 v169, 0x3d372713, v167
	v_mul_f32_e32 v168, v166, v168
	v_mul_f32_e32 v169, v167, v169
	v_fma_f32 v168, v166, v168, v166
	v_fma_f32 v169, v167, v169, v167
	v_mul_f32_e32 v168, 0xbfcc422a, v168
	v_mul_f32_e32 v169, 0xbfcc422a, v169
	v_mul_f32_e32 v168, 0x3fb8aa3b, v168
	v_mul_f32_e32 v169, 0x3fb8aa3b, v169
	v_exp_f32_e32 v168, v168
	v_exp_f32_e32 v169, v169
	global_load_dwordx4 v[66:69], v[170:171], off nt
	v_pk_fma_f32 v[170:171], v[150:151], v[176:177], v[144:145]
	v_add_f32_e32 v168, 1.0, v168
	v_add_f32_e32 v169, 1.0, v169
	v_rcp_f32_e32 v168, v168
	v_rcp_f32_e32 v169, v169
	v_pk_fma_f32 v[170:171], v[24:25], v[130:131], v[170:171]
	v_cvt_pk_bf16_f32 v160, v160, v161
	v_pk_fma_f32 v[170:171], v[40:41], v[178:179], v[170:171]
	v_pk_mul_f32 v[166:167], v[166:167], v[168:169]
	v_cvt_pk_bf16_f32 v161, v162, v163
	v_pk_mul_f32 v[166:167], v[170:171], v[166:167]
	v_cvt_pk_bf16_f32 v162, v164, v165
	v_cvt_pk_bf16_f32 v163, v166, v167
	v_mad_i64_i32 v[164:165], s[0:1], v218, s17, v[154:155]
	global_load_dwordx4 v[50:53], v[172:173], off nt
	global_store_dwordx4 v[164:165], v[160:163], off nt
	s_waitcnt vmcnt(19)
	v_pk_fma_f32 v[164:165], v[138:139], v[214:215], v[136:137]
	v_lshlrev_b32_e32 v176, 16, v54
	v_or_b32_e32 v160, 1, v175
	v_mad_i64_i32 v[194:195], s[0:1], v160, s15, v[152:153]
	v_pk_fma_f32 v[160:161], v[6:7], v[212:213], v[46:47]
	v_and_b32_e32 v177, 0xffff0000, v54
	v_pk_fma_f32 v[160:161], v[14:15], v[192:193], v[160:161]
	v_lshlrev_b32_e32 v172, 16, v55
	v_pk_fma_f32 v[160:161], v[30:31], v[176:177], v[160:161]
	v_and_b32_e32 v173, 0xffff0000, v55
	v_mul_f32_e32 v54, 0x3d372713, v160
	v_mul_f32_e32 v54, v160, v54
	v_fma_f32 v54, v160, v54, v160
	v_mul_f32_e32 v54, 0xbfcc422a, v54
	v_mul_f32_e32 v54, 0x3fb8aa3b, v54
	v_exp_f32_e32 v54, v54
	v_lshlrev_b32_e32 v166, 16, v70
	v_and_b32_e32 v167, 0xffff0000, v70
	v_pk_fma_f32 v[164:165], v[18:19], v[190:191], v[164:165]
	v_add_f32_e32 v54, 1.0, v54
	v_rcp_f32_e32 v162, v54
	v_mul_f32_e32 v54, 0x3d372713, v161
	v_mul_f32_e32 v54, v161, v54
	v_fma_f32 v54, v161, v54, v161
	v_mul_f32_e32 v54, 0xbfcc422a, v54
	v_mul_f32_e32 v54, 0x3fb8aa3b, v54
	v_exp_f32_e32 v54, v54
	v_pk_fma_f32 v[164:165], v[34:35], v[166:167], v[164:165]
	v_lshlrev_b32_e32 v170, 16, v56
	v_and_b32_e32 v171, 0xffff0000, v56
	v_add_f32_e32 v54, 1.0, v54
	v_rcp_f32_e32 v163, v54
	v_pk_fma_f32 v[54:55], v[8:9], v[204:205], v[48:49]
	v_pk_fma_f32 v[132:133], v[4:5], v[132:133], v[44:45]
	v_pk_fma_f32 v[54:55], v[16:17], v[188:189], v[54:55]
	v_pk_mul_f32 v[160:161], v[160:161], v[162:163]
	v_pk_fma_f32 v[54:55], v[32:33], v[172:173], v[54:55]
	v_pk_mul_f32 v[202:203], v[164:165], v[160:161]
	v_lshlrev_b32_e32 v164, 16, v71
	v_and_b32_e32 v165, 0xffff0000, v71
	v_mul_f32_e32 v70, 0x3d372713, v54
	v_mul_f32_e32 v71, 0x3d372713, v55
	v_mul_f32_e32 v70, v54, v70
	v_mul_f32_e32 v71, v55, v71
	v_fma_f32 v70, v54, v70, v54
	v_fma_f32 v71, v55, v71, v55
	v_mul_f32_e32 v70, 0xbfcc422a, v70
	v_mul_f32_e32 v71, 0xbfcc422a, v71
	v_mul_f32_e32 v70, 0x3fb8aa3b, v70
	v_mul_f32_e32 v71, 0x3fb8aa3b, v71
	v_exp_f32_e32 v70, v70
	v_exp_f32_e32 v71, v71
	v_pk_fma_f32 v[160:161], v[146:147], v[206:207], v[140:141]
	v_lshlrev_b32_e32 v162, 16, v72
	v_add_f32_e32 v70, 1.0, v70
	v_add_f32_e32 v71, 1.0, v71
	v_rcp_f32_e32 v70, v70
	v_rcp_f32_e32 v71, v71
	v_pk_fma_f32 v[160:161], v[20:21], v[186:187], v[160:161]
	v_and_b32_e32 v163, 0xffff0000, v72
	v_pk_fma_f32 v[160:161], v[36:37], v[164:165], v[160:161]
	v_pk_mul_f32 v[54:55], v[54:55], v[70:71]
	v_lshlrev_b32_e32 v168, 16, v57
	v_pk_mul_f32 v[204:205], v[160:161], v[54:55]
	v_pk_fma_f32 v[54:55], v[2:3], v[196:197], v[42:43]
	v_pk_fma_f32 v[160:161], v[148:149], v[198:199], v[142:143]
	v_pk_fma_f32 v[54:55], v[10:11], v[184:185], v[54:55]
	v_pk_fma_f32 v[160:161], v[22:23], v[182:183], v[160:161]
	v_pk_fma_f32 v[54:55], v[26:27], v[170:171], v[54:55]
	v_pk_fma_f32 v[160:161], v[38:39], v[162:163], v[160:161]
	v_mul_f32_e32 v56, 0x3d372713, v54
	v_mul_f32_e32 v56, v54, v56
	v_fma_f32 v56, v54, v56, v54
	v_mul_f32_e32 v56, 0xbfcc422a, v56
	v_mul_f32_e32 v56, 0x3fb8aa3b, v56
	v_exp_f32_e32 v56, v56
	v_and_b32_e32 v169, 0xffff0000, v57
	v_pk_fma_f32 v[132:133], v[12:13], v[180:181], v[132:133]
	v_lshl_add_u64 v[200:201], v[194:195], 0, s[8:9]
	v_add_f32_e32 v56, 1.0, v56
	v_rcp_f32_e32 v70, v56
	v_mul_f32_e32 v56, 0x3d372713, v55
	v_mul_f32_e32 v56, v55, v56
	v_fma_f32 v56, v55, v56, v55
	v_mul_f32_e32 v56, 0xbfcc422a, v56
	v_mul_f32_e32 v56, 0x3fb8aa3b, v56
	v_exp_f32_e32 v56, v56
	v_pk_fma_f32 v[132:133], v[28:29], v[168:169], v[132:133]
	v_pk_fma_f32 v[130:131], v[150:151], v[130:131], v[144:145]
	v_pk_fma_f32 v[192:193], v[6:7], v[192:193], v[46:47]
	v_add_f32_e32 v56, 1.0, v56
	v_rcp_f32_e32 v71, v56
	v_pk_fma_f32 v[130:131], v[24:25], v[178:179], v[130:131]
	v_pk_fma_f32 v[192:193], v[14:15], v[176:177], v[192:193]
	v_pk_fma_f32 v[190:191], v[138:139], v[190:191], v[136:137]
	v_pk_mul_f32 v[54:55], v[54:55], v[70:71]
	v_pk_fma_f32 v[190:191], v[18:19], v[166:167], v[190:191]
	v_pk_mul_f32 v[196:197], v[160:161], v[54:55]
	v_lshlrev_b32_e32 v160, 16, v73
	v_and_b32_e32 v161, 0xffff0000, v73
	global_load_dwordx4 v[54:57], v[194:195], off nt
	v_mul_f32_e32 v194, 0x3d372713, v132
	v_mul_f32_e32 v195, 0x3d372713, v133
	v_mul_f32_e32 v194, v132, v194
	v_mul_f32_e32 v195, v133, v195
	v_fma_f32 v194, v132, v194, v132
	v_fma_f32 v195, v133, v195, v133
	v_mul_f32_e32 v194, 0xbfcc422a, v194
	v_mul_f32_e32 v195, 0xbfcc422a, v195
	v_mul_f32_e32 v194, 0x3fb8aa3b, v194
	v_mul_f32_e32 v195, 0x3fb8aa3b, v195
	v_exp_f32_e32 v194, v194
	v_exp_f32_e32 v195, v195
	v_pk_fma_f32 v[130:131], v[40:41], v[160:161], v[130:131]
	global_load_dwordx4 v[70:73], v[200:201], off nt
	v_add_f32_e32 v194, 1.0, v194
	v_add_f32_e32 v195, 1.0, v195
	v_rcp_f32_e32 v194, v194
	v_rcp_f32_e32 v195, v195
	v_pk_fma_f32 v[186:187], v[146:147], v[186:187], v[140:141]
	v_pk_fma_f32 v[182:183], v[148:149], v[182:183], v[142:143]
	v_pk_fma_f32 v[186:187], v[20:21], v[164:165], v[186:187]
	v_pk_mul_f32 v[132:133], v[132:133], v[194:195]
	v_pk_fma_f32 v[182:183], v[22:23], v[162:163], v[182:183]
	v_pk_mul_f32 v[194:195], v[130:131], v[132:133]
	v_cvt_pk_bf16_f32 v130, v202, v203
	v_cvt_pk_bf16_f32 v133, v194, v195
	v_add_u32_e32 v194, -6, v135
	v_cvt_pk_bf16_f32 v131, v204, v205
	v_cvt_pk_bf16_f32 v132, v196, v197
	v_mad_i64_i32 v[194:195], s[0:1], v194, s17, v[154:155]
	global_store_dwordx4 v[194:195], v[130:133], off nt
	s_waitcnt vmcnt(20)
	v_pk_fma_f32 v[178:179], v[150:151], v[178:179], v[144:145]
	v_lshlrev_b32_e32 v196, 16, v82
	v_and_b32_e32 v197, 0xffff0000, v82
	v_pk_fma_f32 v[192:193], v[30:31], v[196:197], v[192:193]
	v_lshlrev_b32_e32 v208, 16, v83
	v_mul_f32_e32 v82, 0x3d372713, v192
	v_mul_f32_e32 v82, v192, v82
	v_fma_f32 v82, v192, v82, v192
	v_mul_f32_e32 v82, 0xbfcc422a, v82
	v_mul_f32_e32 v82, 0x3fb8aa3b, v82
	v_exp_f32_e32 v82, v82
	v_and_b32_e32 v209, 0xffff0000, v83
	v_lshlrev_b32_e32 v194, 16, v86
	v_and_b32_e32 v195, 0xffff0000, v86
	v_add_f32_e32 v82, 1.0, v82
	v_rcp_f32_e32 v198, v82
	v_mul_f32_e32 v82, 0x3d372713, v193
	v_mul_f32_e32 v82, v193, v82
	v_fma_f32 v82, v193, v82, v193
	v_mul_f32_e32 v82, 0xbfcc422a, v82
	v_mul_f32_e32 v82, 0x3fb8aa3b, v82
	v_exp_f32_e32 v82, v82
	v_pk_fma_f32 v[190:191], v[34:35], v[194:195], v[190:191]
	v_lshlrev_b32_e32 v206, 16, v84
	v_and_b32_e32 v207, 0xffff0000, v84
	v_add_f32_e32 v82, 1.0, v82
	v_rcp_f32_e32 v199, v82
	v_pk_fma_f32 v[82:83], v[8:9], v[188:189], v[48:49]
	v_or_b32_e32 v130, 2, v175
	v_pk_fma_f32 v[82:83], v[16:17], v[172:173], v[82:83]
	v_pk_mul_f32 v[192:193], v[192:193], v[198:199]
	v_pk_fma_f32 v[82:83], v[32:33], v[208:209], v[82:83]
	v_pk_mul_f32 v[198:199], v[190:191], v[192:193]
	v_lshlrev_b32_e32 v190, 16, v87
	v_and_b32_e32 v191, 0xffff0000, v87
	v_mul_f32_e32 v86, 0x3d372713, v82
	v_mul_f32_e32 v87, 0x3d372713, v83
	v_mul_f32_e32 v86, v82, v86
	v_mul_f32_e32 v87, v83, v87
	v_fma_f32 v86, v82, v86, v82
	v_fma_f32 v87, v83, v87, v83
	v_mul_f32_e32 v86, 0xbfcc422a, v86
	v_mul_f32_e32 v87, 0xbfcc422a, v87
	v_mul_f32_e32 v86, 0x3fb8aa3b, v86
	v_mul_f32_e32 v87, 0x3fb8aa3b, v87
	v_exp_f32_e32 v86, v86
	v_exp_f32_e32 v87, v87
	v_pk_fma_f32 v[186:187], v[36:37], v[190:191], v[186:187]
	v_mad_i64_i32 v[130:131], s[0:1], v130, s15, v[152:153]
	v_add_f32_e32 v86, 1.0, v86
	v_add_f32_e32 v87, 1.0, v87
	v_rcp_f32_e32 v86, v86
	v_rcp_f32_e32 v87, v87
	v_lshlrev_b32_e32 v192, 16, v85
	v_and_b32_e32 v193, 0xffff0000, v85
	v_lshl_add_u64 v[132:133], v[130:131], 0, s[8:9]
	v_pk_mul_f32 v[82:83], v[82:83], v[86:87]
	v_pk_fma_f32 v[178:179], v[24:25], v[160:161], v[178:179]
	v_pk_mul_f32 v[188:189], v[186:187], v[82:83]
	v_pk_fma_f32 v[82:83], v[2:3], v[184:185], v[42:43]
	v_lshlrev_b32_e32 v186, 16, v88
	v_pk_fma_f32 v[82:83], v[10:11], v[170:171], v[82:83]
	v_and_b32_e32 v187, 0xffff0000, v88
	v_pk_fma_f32 v[82:83], v[26:27], v[206:207], v[82:83]
	v_pk_fma_f32 v[182:183], v[38:39], v[186:187], v[182:183]
	v_mul_f32_e32 v84, 0x3d372713, v82
	v_mul_f32_e32 v84, v82, v84
	v_fma_f32 v84, v82, v84, v82
	v_mul_f32_e32 v84, 0xbfcc422a, v84
	v_mul_f32_e32 v84, 0x3fb8aa3b, v84
	v_exp_f32_e32 v84, v84
	v_pk_fma_f32 v[176:177], v[6:7], v[176:177], v[46:47]
	v_pk_fma_f32 v[166:167], v[138:139], v[166:167], v[136:137]
	v_pk_fma_f32 v[176:177], v[14:15], v[196:197], v[176:177]
	v_add_f32_e32 v84, 1.0, v84
	v_rcp_f32_e32 v86, v84
	v_mul_f32_e32 v84, 0x3d372713, v83
	v_mul_f32_e32 v84, v83, v84
	v_fma_f32 v84, v83, v84, v83
	v_mul_f32_e32 v84, 0xbfcc422a, v84
	v_mul_f32_e32 v84, 0x3fb8aa3b, v84
	v_exp_f32_e32 v84, v84
	v_pk_fma_f32 v[166:167], v[18:19], v[194:195], v[166:167]
	v_pk_fma_f32 v[164:165], v[146:147], v[164:165], v[140:141]
	v_pk_fma_f32 v[162:163], v[148:149], v[162:163], v[142:143]
	v_add_f32_e32 v84, 1.0, v84
	v_rcp_f32_e32 v87, v84
	v_pk_fma_f32 v[164:165], v[20:21], v[190:191], v[164:165]
	v_pk_fma_f32 v[162:163], v[22:23], v[186:187], v[162:163]
	v_pk_fma_f32 v[160:161], v[150:151], v[160:161], v[144:145]
	v_pk_mul_f32 v[82:83], v[82:83], v[86:87]
	s_or_b64 s[12:13], vcc, s[12:13]
	v_pk_mul_f32 v[184:185], v[182:183], v[82:83]
	v_lshlrev_b32_e32 v182, 16, v89
	v_and_b32_e32 v183, 0xffff0000, v89
	global_load_dwordx4 v[82:85], v[130:131], off nt
	v_pk_fma_f32 v[130:131], v[4:5], v[180:181], v[44:45]
	global_load_dwordx4 v[86:89], v[132:133], off nt
	v_pk_fma_f32 v[178:179], v[40:41], v[182:183], v[178:179]
	v_pk_fma_f32 v[130:131], v[12:13], v[168:169], v[130:131]
	v_pk_fma_f32 v[160:161], v[24:25], v[182:183], v[160:161]
	v_pk_fma_f32 v[130:131], v[28:29], v[192:193], v[130:131]
	v_pk_fma_f32 v[182:183], v[150:151], v[182:183], v[144:145]
	v_mul_f32_e32 v132, 0x3d372713, v130
	v_mul_f32_e32 v133, 0x3d372713, v131
	v_mul_f32_e32 v132, v130, v132
	v_mul_f32_e32 v133, v131, v133
	v_fma_f32 v132, v130, v132, v130
	v_fma_f32 v133, v131, v133, v131
	v_mul_f32_e32 v132, 0xbfcc422a, v132
	v_mul_f32_e32 v133, 0xbfcc422a, v133
	v_mul_f32_e32 v132, 0x3fb8aa3b, v132
	v_mul_f32_e32 v133, 0x3fb8aa3b, v133
	v_exp_f32_e32 v132, v132
	v_exp_f32_e32 v133, v133
	v_add_f32_e32 v132, 1.0, v132
	v_add_f32_e32 v133, 1.0, v133
	v_rcp_f32_e32 v132, v132
	v_rcp_f32_e32 v133, v133
	s_nop 0
	v_pk_mul_f32 v[130:131], v[130:131], v[132:133]
	s_nop 0
	v_pk_mul_f32 v[178:179], v[178:179], v[130:131]
	v_cvt_pk_bf16_f32 v130, v198, v199
	v_cvt_pk_bf16_f32 v133, v178, v179
	v_add_u32_e32 v178, -5, v135
	v_cvt_pk_bf16_f32 v131, v188, v189
	v_cvt_pk_bf16_f32 v132, v184, v185
	v_mad_i64_i32 v[178:179], s[0:1], v178, s17, v[154:155]
	global_store_dwordx4 v[178:179], v[130:133], off nt
	s_waitcnt vmcnt(21)
	s_nop 0
	v_lshlrev_b32_e32 v204, 16, v90
	v_and_b32_e32 v205, 0xffff0000, v90
	v_pk_fma_f32 v[176:177], v[30:31], v[204:205], v[176:177]
	v_lshlrev_b32_e32 v202, 16, v91
	v_mul_f32_e32 v90, 0x3d372713, v176
	v_mul_f32_e32 v90, v176, v90
	v_fma_f32 v90, v176, v90, v176
	v_mul_f32_e32 v90, 0xbfcc422a, v90
	v_mul_f32_e32 v90, 0x3fb8aa3b, v90
	v_exp_f32_e32 v90, v90
	v_and_b32_e32 v203, 0xffff0000, v91
	v_lshlrev_b32_e32 v184, 16, v94
	v_and_b32_e32 v185, 0xffff0000, v94
	v_add_f32_e32 v90, 1.0, v90
	v_rcp_f32_e32 v178, v90
	v_mul_f32_e32 v90, 0x3d372713, v177
	v_mul_f32_e32 v90, v177, v90
	v_fma_f32 v90, v177, v90, v177
	v_mul_f32_e32 v90, 0xbfcc422a, v90
	v_mul_f32_e32 v90, 0x3fb8aa3b, v90
	v_exp_f32_e32 v90, v90
	v_pk_fma_f32 v[166:167], v[34:35], v[184:185], v[166:167]
	v_lshlrev_b32_e32 v200, 16, v92
	v_and_b32_e32 v201, 0xffff0000, v92
	v_add_f32_e32 v90, 1.0, v90
	v_rcp_f32_e32 v179, v90
	v_pk_fma_f32 v[90:91], v[8:9], v[172:173], v[48:49]
	v_or_b32_e32 v130, 3, v175
	v_pk_fma_f32 v[90:91], v[16:17], v[208:209], v[90:91]
	v_pk_mul_f32 v[176:177], v[176:177], v[178:179]
	v_pk_fma_f32 v[90:91], v[32:33], v[202:203], v[90:91]
	v_pk_mul_f32 v[176:177], v[166:167], v[176:177]
	v_lshlrev_b32_e32 v166, 16, v95
	v_and_b32_e32 v167, 0xffff0000, v95
	v_mul_f32_e32 v94, 0x3d372713, v90
	v_mul_f32_e32 v95, 0x3d372713, v91
	v_mul_f32_e32 v94, v90, v94
	v_mul_f32_e32 v95, v91, v95
	v_fma_f32 v94, v90, v94, v90
	v_fma_f32 v95, v91, v95, v91
	v_mul_f32_e32 v94, 0xbfcc422a, v94
	v_mul_f32_e32 v95, 0xbfcc422a, v95
	v_mul_f32_e32 v94, 0x3fb8aa3b, v94
	v_mul_f32_e32 v95, 0x3fb8aa3b, v95
	v_exp_f32_e32 v94, v94
	v_exp_f32_e32 v95, v95
	v_pk_fma_f32 v[164:165], v[36:37], v[166:167], v[164:165]
	v_lshlrev_b32_e32 v180, 16, v96
	v_add_f32_e32 v94, 1.0, v94
	v_add_f32_e32 v95, 1.0, v95
	v_rcp_f32_e32 v94, v94
	v_rcp_f32_e32 v95, v95
	v_and_b32_e32 v181, 0xffff0000, v96
	v_mad_i64_i32 v[130:131], s[0:1], v130, s15, v[152:153]
	v_pk_mul_f32 v[90:91], v[90:91], v[94:95]
	v_pk_fma_f32 v[162:163], v[38:39], v[180:181], v[162:163]
	v_pk_mul_f32 v[172:173], v[164:165], v[90:91]
	v_pk_fma_f32 v[90:91], v[2:3], v[170:171], v[42:43]
	v_lshlrev_b32_e32 v188, 16, v93
	v_pk_fma_f32 v[90:91], v[10:11], v[206:207], v[90:91]
	v_and_b32_e32 v189, 0xffff0000, v93
	v_pk_fma_f32 v[90:91], v[26:27], v[200:201], v[90:91]
	v_lshlrev_b32_e32 v164, 16, v97
	v_mul_f32_e32 v92, 0x3d372713, v90
	v_mul_f32_e32 v92, v90, v92
	v_fma_f32 v92, v90, v92, v90
	v_mul_f32_e32 v92, 0xbfcc422a, v92
	v_mul_f32_e32 v92, 0x3fb8aa3b, v92
	v_exp_f32_e32 v92, v92
	v_and_b32_e32 v165, 0xffff0000, v97
	v_lshl_add_u64 v[132:133], v[130:131], 0, s[8:9]
	v_add_f32_e32 v92, 1.0, v92
	v_rcp_f32_e32 v94, v92
	v_mul_f32_e32 v92, 0x3d372713, v91
	v_mul_f32_e32 v92, v91, v92
	v_fma_f32 v92, v91, v92, v91
	v_mul_f32_e32 v92, 0xbfcc422a, v92
	v_mul_f32_e32 v92, 0x3fb8aa3b, v92
	v_exp_f32_e32 v92, v92
	v_pk_fma_f32 v[160:161], v[40:41], v[164:165], v[160:161]
	v_pk_fma_f32 v[182:183], v[24:25], v[164:165], v[182:183]
	v_pk_fma_f32 v[164:165], v[150:151], v[164:165], v[144:145]
	v_add_f32_e32 v92, 1.0, v92
	v_rcp_f32_e32 v95, v92
	s_nop 0
	v_pk_mul_f32 v[90:91], v[90:91], v[94:95]
	s_nop 0
	v_pk_mul_f32 v[162:163], v[162:163], v[90:91]
	global_load_dwordx4 v[90:93], v[130:131], off nt
	v_pk_fma_f32 v[130:131], v[4:5], v[168:169], v[44:45]
	global_load_dwordx4 v[94:97], v[132:133], off nt
	v_pk_fma_f32 v[168:169], v[138:139], v[194:195], v[136:137]
	v_pk_fma_f32 v[130:131], v[12:13], v[192:193], v[130:131]
	v_pk_fma_f32 v[168:169], v[18:19], v[184:185], v[168:169]
	v_pk_fma_f32 v[130:131], v[28:29], v[188:189], v[130:131]
	s_nop 0
	v_mul_f32_e32 v132, 0x3d372713, v130
	v_mul_f32_e32 v133, 0x3d372713, v131
	v_mul_f32_e32 v132, v130, v132
	v_mul_f32_e32 v133, v131, v133
	v_fma_f32 v132, v130, v132, v130
	v_fma_f32 v133, v131, v133, v131
	v_mul_f32_e32 v132, 0xbfcc422a, v132
	v_mul_f32_e32 v133, 0xbfcc422a, v133
	v_mul_f32_e32 v132, 0x3fb8aa3b, v132
	v_mul_f32_e32 v133, 0x3fb8aa3b, v133
	v_exp_f32_e32 v132, v132
	v_exp_f32_e32 v133, v133
	v_add_f32_e32 v132, 1.0, v132
	v_add_f32_e32 v133, 1.0, v133
	v_rcp_f32_e32 v132, v132
	v_rcp_f32_e32 v133, v133
	s_nop 0
	v_pk_mul_f32 v[130:131], v[130:131], v[132:133]
	s_nop 0
	v_pk_mul_f32 v[160:161], v[160:161], v[130:131]
	v_cvt_pk_bf16_f32 v130, v176, v177
	v_cvt_pk_bf16_f32 v133, v160, v161
	v_add_u32_e32 v160, -4, v135
	v_cvt_pk_bf16_f32 v131, v172, v173
	v_cvt_pk_bf16_f32 v132, v162, v163
	v_mad_i64_i32 v[160:161], s[0:1], v160, s17, v[154:155]
	global_store_dwordx4 v[160:161], v[130:133], off nt
	v_pk_fma_f32 v[160:161], v[6:7], v[196:197], v[46:47]
	s_waitcnt vmcnt(22)
	s_nop 0
	v_lshlrev_b32_e32 v198, 16, v98
	v_and_b32_e32 v199, 0xffff0000, v98
	v_pk_fma_f32 v[160:161], v[14:15], v[204:205], v[160:161]
	v_lshlrev_b32_e32 v196, 16, v99
	v_pk_fma_f32 v[160:161], v[30:31], v[198:199], v[160:161]
	v_and_b32_e32 v197, 0xffff0000, v99
	v_mul_f32_e32 v98, 0x3d372713, v160
	v_mul_f32_e32 v98, v160, v98
	v_fma_f32 v98, v160, v98, v160
	v_mul_f32_e32 v98, 0xbfcc422a, v98
	v_mul_f32_e32 v98, 0x3fb8aa3b, v98
	v_exp_f32_e32 v98, v98
	v_lshlrev_b32_e32 v178, 16, v102
	v_and_b32_e32 v179, 0xffff0000, v102
	v_lshlrev_b32_e32 v176, 16, v103
	v_add_f32_e32 v98, 1.0, v98
	v_rcp_f32_e32 v162, v98
	v_mul_f32_e32 v98, 0x3d372713, v161
	v_mul_f32_e32 v98, v161, v98
	v_fma_f32 v98, v161, v98, v161
	v_mul_f32_e32 v98, 0xbfcc422a, v98
	v_mul_f32_e32 v98, 0x3fb8aa3b, v98
	v_exp_f32_e32 v98, v98
	v_and_b32_e32 v177, 0xffff0000, v103
	v_pk_fma_f32 v[168:169], v[34:35], v[178:179], v[168:169]
	v_lshlrev_b32_e32 v194, 16, v100
	v_add_f32_e32 v98, 1.0, v98
	v_rcp_f32_e32 v163, v98
	v_pk_fma_f32 v[98:99], v[8:9], v[208:209], v[48:49]
	v_and_b32_e32 v195, 0xffff0000, v100
	v_pk_fma_f32 v[98:99], v[16:17], v[202:203], v[98:99]
	v_pk_mul_f32 v[160:161], v[160:161], v[162:163]
	v_pk_fma_f32 v[98:99], v[32:33], v[196:197], v[98:99]
	v_pk_fma_f32 v[162:163], v[146:147], v[190:191], v[140:141]
	v_mul_f32_e32 v102, 0x3d372713, v98
	v_mul_f32_e32 v103, 0x3d372713, v99
	v_mul_f32_e32 v102, v98, v102
	v_mul_f32_e32 v103, v99, v103
	v_fma_f32 v102, v98, v102, v98
	v_fma_f32 v103, v99, v103, v99
	v_mul_f32_e32 v102, 0xbfcc422a, v102
	v_mul_f32_e32 v103, 0xbfcc422a, v103
	v_mul_f32_e32 v102, 0x3fb8aa3b, v102
	v_mul_f32_e32 v103, 0x3fb8aa3b, v103
	v_exp_f32_e32 v102, v102
	v_exp_f32_e32 v103, v103
	v_pk_fma_f32 v[162:163], v[20:21], v[166:167], v[162:163]
	v_pk_mul_f32 v[160:161], v[168:169], v[160:161]
	v_add_f32_e32 v102, 1.0, v102
	v_add_f32_e32 v103, 1.0, v103
	v_rcp_f32_e32 v102, v102
	v_rcp_f32_e32 v103, v103
	v_pk_fma_f32 v[162:163], v[36:37], v[176:177], v[162:163]
	v_lshlrev_b32_e32 v172, 16, v104
	v_and_b32_e32 v173, 0xffff0000, v104
	v_pk_mul_f32 v[98:99], v[98:99], v[102:103]
	v_or_b32_e32 v130, 4, v175
	v_pk_mul_f32 v[168:169], v[162:163], v[98:99]
	v_pk_fma_f32 v[98:99], v[2:3], v[206:207], v[42:43]
	v_pk_fma_f32 v[162:163], v[148:149], v[186:187], v[142:143]
	v_pk_fma_f32 v[98:99], v[10:11], v[200:201], v[98:99]
	v_pk_fma_f32 v[162:163], v[22:23], v[180:181], v[162:163]
	v_pk_fma_f32 v[98:99], v[26:27], v[194:195], v[98:99]
	v_pk_fma_f32 v[162:163], v[38:39], v[172:173], v[162:163]
	v_mul_f32_e32 v100, 0x3d372713, v98
	v_mul_f32_e32 v100, v98, v100
	v_fma_f32 v100, v98, v100, v98
	v_mul_f32_e32 v100, 0xbfcc422a, v100
	v_mul_f32_e32 v100, 0x3fb8aa3b, v100
	v_exp_f32_e32 v100, v100
	v_mad_i64_i32 v[130:131], s[0:1], v130, s15, v[152:153]
	v_lshlrev_b32_e32 v186, 16, v101
	v_add_f32_e32 v100, 1.0, v100
	v_rcp_f32_e32 v102, v100
	v_mul_f32_e32 v100, 0x3d372713, v99
	v_mul_f32_e32 v100, v99, v100
	v_fma_f32 v100, v99, v100, v99
	v_mul_f32_e32 v100, 0xbfcc422a, v100
	v_mul_f32_e32 v100, 0x3fb8aa3b, v100
	v_exp_f32_e32 v100, v100
	v_and_b32_e32 v187, 0xffff0000, v101
	v_lshl_add_u64 v[132:133], v[130:131], 0, s[8:9]
	v_add_f32_e32 v100, 1.0, v100
	v_rcp_f32_e32 v103, v100
	s_nop 0
	v_pk_mul_f32 v[98:99], v[98:99], v[102:103]
	s_nop 0
	v_pk_mul_f32 v[170:171], v[162:163], v[98:99]
	v_lshlrev_b32_e32 v162, 16, v105
	v_and_b32_e32 v163, 0xffff0000, v105
	global_load_dwordx4 v[98:101], v[130:131], off nt
	v_pk_fma_f32 v[130:131], v[4:5], v[192:193], v[44:45]
	global_load_dwordx4 v[102:105], v[132:133], off nt
	v_pk_fma_f32 v[182:183], v[40:41], v[162:163], v[182:183]
	v_pk_fma_f32 v[130:131], v[12:13], v[188:189], v[130:131]
	v_pk_fma_f32 v[164:165], v[24:25], v[162:163], v[164:165]
	v_pk_fma_f32 v[130:131], v[28:29], v[186:187], v[130:131]
	v_pk_fma_f32 v[162:163], v[150:151], v[162:163], v[144:145]
	v_mul_f32_e32 v132, 0x3d372713, v130
	v_mul_f32_e32 v133, 0x3d372713, v131
	v_mul_f32_e32 v132, v130, v132
	v_mul_f32_e32 v133, v131, v133
	v_fma_f32 v132, v130, v132, v130
	v_fma_f32 v133, v131, v133, v131
	v_mul_f32_e32 v132, 0xbfcc422a, v132
	v_mul_f32_e32 v133, 0xbfcc422a, v133
	v_mul_f32_e32 v132, 0x3fb8aa3b, v132
	v_mul_f32_e32 v133, 0x3fb8aa3b, v133
	v_exp_f32_e32 v132, v132
	v_exp_f32_e32 v133, v133
	v_add_f32_e32 v132, 1.0, v132
	v_add_f32_e32 v133, 1.0, v133
	v_rcp_f32_e32 v132, v132
	v_rcp_f32_e32 v133, v133
	s_nop 0
	v_pk_mul_f32 v[130:131], v[130:131], v[132:133]
	s_nop 0
	v_pk_mul_f32 v[182:183], v[182:183], v[130:131]
	v_cvt_pk_bf16_f32 v130, v160, v161
	v_add_u32_e32 v160, -3, v135
	v_cvt_pk_bf16_f32 v131, v168, v169
	v_cvt_pk_bf16_f32 v132, v170, v171
	v_cvt_pk_bf16_f32 v133, v182, v183
	v_mad_i64_i32 v[160:161], s[0:1], v160, s17, v[154:155]
	global_store_dwordx4 v[160:161], v[130:133], off nt
	v_pk_fma_f32 v[160:161], v[6:7], v[204:205], v[46:47]
	s_waitcnt vmcnt(23)
	v_pk_fma_f32 v[182:183], v[138:139], v[184:185], v[136:137]
	v_lshlrev_b32_e32 v190, 16, v106
	v_and_b32_e32 v191, 0xffff0000, v106
	v_pk_fma_f32 v[160:161], v[14:15], v[198:199], v[160:161]
	v_lshlrev_b32_e32 v184, 16, v107
	v_pk_fma_f32 v[160:161], v[30:31], v[190:191], v[160:161]
	v_and_b32_e32 v185, 0xffff0000, v107
	v_mul_f32_e32 v106, 0x3d372713, v160
	v_mul_f32_e32 v106, v160, v106
	v_fma_f32 v106, v160, v106, v160
	v_mul_f32_e32 v106, 0xbfcc422a, v106
	v_mul_f32_e32 v106, 0x3fb8aa3b, v106
	v_exp_f32_e32 v106, v106
	v_lshlrev_b32_e32 v170, 16, v110
	v_and_b32_e32 v171, 0xffff0000, v110
	v_pk_fma_f32 v[182:183], v[18:19], v[178:179], v[182:183]
	v_add_f32_e32 v106, 1.0, v106
	v_rcp_f32_e32 v168, v106
	v_mul_f32_e32 v106, 0x3d372713, v161
	v_mul_f32_e32 v106, v161, v106
	v_fma_f32 v106, v161, v106, v161
	v_mul_f32_e32 v106, 0xbfcc422a, v106
	v_mul_f32_e32 v106, 0x3fb8aa3b, v106
	v_exp_f32_e32 v106, v106
	v_pk_fma_f32 v[182:183], v[34:35], v[170:171], v[182:183]
	v_or_b32_e32 v130, 5, v175
	v_mad_i64_i32 v[130:131], s[0:1], v130, s15, v[152:153]
	v_add_f32_e32 v106, 1.0, v106
	v_rcp_f32_e32 v169, v106
	v_pk_fma_f32 v[106:107], v[8:9], v[202:203], v[48:49]
	v_lshl_add_u64 v[132:133], v[130:131], 0, s[8:9]
	v_pk_fma_f32 v[106:107], v[16:17], v[196:197], v[106:107]
	v_pk_mul_f32 v[160:161], v[160:161], v[168:169]
	v_pk_fma_f32 v[106:107], v[32:33], v[184:185], v[106:107]
	v_lshlrev_b32_e32 v168, 16, v111
	v_and_b32_e32 v169, 0xffff0000, v111
	v_mul_f32_e32 v110, 0x3d372713, v106
	v_mul_f32_e32 v111, 0x3d372713, v107
	v_mul_f32_e32 v110, v106, v110
	v_mul_f32_e32 v111, v107, v111
	v_fma_f32 v110, v106, v110, v106
	v_fma_f32 v111, v107, v111, v107
	v_mul_f32_e32 v110, 0xbfcc422a, v110
	v_mul_f32_e32 v111, 0xbfcc422a, v111
	v_mul_f32_e32 v110, 0x3fb8aa3b, v110
	v_mul_f32_e32 v111, 0x3fb8aa3b, v111
	v_exp_f32_e32 v110, v110
	v_exp_f32_e32 v111, v111
	v_pk_mul_f32 v[192:193], v[182:183], v[160:161]
	v_pk_fma_f32 v[160:161], v[146:147], v[166:167], v[140:141]
	v_add_f32_e32 v110, 1.0, v110
	v_add_f32_e32 v111, 1.0, v111
	v_rcp_f32_e32 v110, v110
	v_rcp_f32_e32 v111, v111
	v_pk_fma_f32 v[160:161], v[20:21], v[176:177], v[160:161]
	v_lshlrev_b32_e32 v182, 16, v108
	v_pk_fma_f32 v[160:161], v[36:37], v[168:169], v[160:161]
	v_pk_mul_f32 v[106:107], v[106:107], v[110:111]
	v_and_b32_e32 v183, 0xffff0000, v108
	v_pk_mul_f32 v[202:203], v[160:161], v[106:107]
	v_pk_fma_f32 v[106:107], v[2:3], v[200:201], v[42:43]
	v_pk_fma_f32 v[160:161], v[148:149], v[180:181], v[142:143]
	v_pk_fma_f32 v[106:107], v[10:11], v[194:195], v[106:107]
	v_lshlrev_b32_e32 v166, 16, v112
	v_pk_fma_f32 v[106:107], v[26:27], v[182:183], v[106:107]
	v_and_b32_e32 v167, 0xffff0000, v112
	v_mul_f32_e32 v108, 0x3d372713, v106
	v_mul_f32_e32 v108, v106, v108
	v_fma_f32 v108, v106, v108, v106
	v_mul_f32_e32 v108, 0xbfcc422a, v108
	v_mul_f32_e32 v108, 0x3fb8aa3b, v108
	v_exp_f32_e32 v108, v108
	v_pk_fma_f32 v[160:161], v[22:23], v[172:173], v[160:161]
	v_lshlrev_b32_e32 v180, 16, v109
	v_pk_fma_f32 v[160:161], v[38:39], v[166:167], v[160:161]
	v_add_f32_e32 v108, 1.0, v108
	v_rcp_f32_e32 v110, v108
	v_mul_f32_e32 v108, 0x3d372713, v107
	v_mul_f32_e32 v108, v107, v108
	v_fma_f32 v108, v107, v108, v107
	v_mul_f32_e32 v108, 0xbfcc422a, v108
	v_mul_f32_e32 v108, 0x3fb8aa3b, v108
	v_exp_f32_e32 v108, v108
	v_and_b32_e32 v181, 0xffff0000, v109
	v_pk_fma_f32 v[178:179], v[138:139], v[178:179], v[136:137]
	v_add_f32_e32 v108, 1.0, v108
	v_rcp_f32_e32 v111, v108
	v_pk_fma_f32 v[178:179], v[18:19], v[170:171], v[178:179]
	v_pk_mul_f32 v[106:107], v[106:107], v[110:111]
	s_nop 0
	v_pk_mul_f32 v[200:201], v[160:161], v[106:107]
	v_lshlrev_b32_e32 v160, 16, v113
	v_and_b32_e32 v161, 0xffff0000, v113
	global_load_dwordx4 v[106:109], v[130:131], off nt
	v_pk_fma_f32 v[130:131], v[4:5], v[188:189], v[44:45]
	global_load_dwordx4 v[110:113], v[132:133], off nt
	v_pk_fma_f32 v[164:165], v[40:41], v[160:161], v[164:165]
	v_pk_fma_f32 v[130:131], v[12:13], v[186:187], v[130:131]
	v_pk_fma_f32 v[162:163], v[24:25], v[160:161], v[162:163]
	v_pk_fma_f32 v[130:131], v[28:29], v[180:181], v[130:131]
	v_pk_fma_f32 v[170:171], v[138:139], v[170:171], v[136:137]
	v_mul_f32_e32 v132, 0x3d372713, v130
	v_mul_f32_e32 v133, 0x3d372713, v131
	v_mul_f32_e32 v132, v130, v132
	v_mul_f32_e32 v133, v131, v133
	v_fma_f32 v132, v130, v132, v130
	v_fma_f32 v133, v131, v133, v131
	v_mul_f32_e32 v132, 0xbfcc422a, v132
	v_mul_f32_e32 v133, 0xbfcc422a, v133
	v_mul_f32_e32 v132, 0x3fb8aa3b, v132
	v_mul_f32_e32 v133, 0x3fb8aa3b, v133
	v_exp_f32_e32 v132, v132
	v_exp_f32_e32 v133, v133
	v_pk_fma_f32 v[160:161], v[150:151], v[160:161], v[144:145]
	v_add_f32_e32 v132, 1.0, v132
	v_add_f32_e32 v133, 1.0, v133
	v_rcp_f32_e32 v132, v132
	v_rcp_f32_e32 v133, v133
	s_nop 0
	v_pk_mul_f32 v[130:131], v[130:131], v[132:133]
	s_nop 0
	v_pk_mul_f32 v[164:165], v[164:165], v[130:131]
	v_cvt_pk_bf16_f32 v130, v192, v193
	v_cvt_pk_bf16_f32 v133, v164, v165
	v_add_u32_e32 v164, -2, v135
	v_cvt_pk_bf16_f32 v131, v202, v203
	v_cvt_pk_bf16_f32 v132, v200, v201
	v_mad_i64_i32 v[164:165], s[0:1], v164, s17, v[154:155]
	global_store_dwordx4 v[164:165], v[130:133], off nt
	v_pk_fma_f32 v[164:165], v[6:7], v[198:199], v[46:47]
	s_waitcnt vmcnt(24)
	s_nop 0
	v_lshlrev_b32_e32 v200, 16, v114
	v_and_b32_e32 v201, 0xffff0000, v114
	v_pk_fma_f32 v[164:165], v[14:15], v[190:191], v[164:165]
	v_lshlrev_b32_e32 v198, 16, v115
	v_pk_fma_f32 v[164:165], v[30:31], v[200:201], v[164:165]
	v_and_b32_e32 v199, 0xffff0000, v115
	v_mul_f32_e32 v114, 0x3d372713, v164
	v_mul_f32_e32 v114, v164, v114
	v_fma_f32 v114, v164, v114, v164
	v_mul_f32_e32 v114, 0xbfcc422a, v114
	v_mul_f32_e32 v114, 0x3fb8aa3b, v114
	v_exp_f32_e32 v114, v114
	v_lshlrev_b32_e32 v188, 16, v118
	v_and_b32_e32 v189, 0xffff0000, v118
	v_pk_fma_f32 v[178:179], v[34:35], v[188:189], v[178:179]
	v_add_f32_e32 v114, 1.0, v114
	v_rcp_f32_e32 v192, v114
	v_mul_f32_e32 v114, 0x3d372713, v165
	v_mul_f32_e32 v114, v165, v114
	v_fma_f32 v114, v165, v114, v165
	v_mul_f32_e32 v114, 0xbfcc422a, v114
	v_mul_f32_e32 v114, 0x3fb8aa3b, v114
	v_exp_f32_e32 v114, v114
	v_or_b32_e32 v130, 6, v175
	v_mad_i64_i32 v[130:131], s[0:1], v130, s15, v[152:153]
	v_add_f32_e32 v114, 1.0, v114
	v_rcp_f32_e32 v193, v114
	v_pk_fma_f32 v[114:115], v[8:9], v[196:197], v[48:49]
	v_lshl_add_u64 v[132:133], v[130:131], 0, s[8:9]
	v_pk_fma_f32 v[114:115], v[16:17], v[184:185], v[114:115]
	v_pk_mul_f32 v[164:165], v[164:165], v[192:193]
	v_pk_fma_f32 v[114:115], v[32:33], v[198:199], v[114:115]
	v_pk_mul_f32 v[202:203], v[178:179], v[164:165]
	v_lshlrev_b32_e32 v178, 16, v119
	v_and_b32_e32 v179, 0xffff0000, v119
	v_mul_f32_e32 v118, 0x3d372713, v114
	v_mul_f32_e32 v119, 0x3d372713, v115
	v_mul_f32_e32 v118, v114, v118
	v_mul_f32_e32 v119, v115, v119
	v_fma_f32 v118, v114, v118, v114
	v_fma_f32 v119, v115, v119, v115
	v_mul_f32_e32 v118, 0xbfcc422a, v118
	v_mul_f32_e32 v119, 0xbfcc422a, v119
	v_mul_f32_e32 v118, 0x3fb8aa3b, v118
	v_mul_f32_e32 v119, 0x3fb8aa3b, v119
	v_exp_f32_e32 v118, v118
	v_exp_f32_e32 v119, v119
	v_pk_fma_f32 v[164:165], v[146:147], v[176:177], v[140:141]
	v_lshlrev_b32_e32 v192, 16, v116
	v_add_f32_e32 v118, 1.0, v118
	v_add_f32_e32 v119, 1.0, v119
	v_rcp_f32_e32 v118, v118
	v_rcp_f32_e32 v119, v119
	v_pk_fma_f32 v[164:165], v[20:21], v[168:169], v[164:165]
	v_and_b32_e32 v193, 0xffff0000, v116
	v_pk_fma_f32 v[164:165], v[36:37], v[178:179], v[164:165]
	v_pk_mul_f32 v[114:115], v[114:115], v[118:119]
	v_lshlrev_b32_e32 v176, 16, v120
	v_pk_mul_f32 v[196:197], v[164:165], v[114:115]
	v_pk_fma_f32 v[114:115], v[2:3], v[194:195], v[42:43]
	v_pk_fma_f32 v[164:165], v[148:149], v[172:173], v[142:143]
	v_pk_fma_f32 v[114:115], v[10:11], v[182:183], v[114:115]
	v_and_b32_e32 v177, 0xffff0000, v120
	v_pk_fma_f32 v[114:115], v[26:27], v[192:193], v[114:115]
	v_pk_fma_f32 v[164:165], v[22:23], v[166:167], v[164:165]
	v_mul_f32_e32 v116, 0x3d372713, v114
	v_mul_f32_e32 v116, v114, v116
	v_fma_f32 v116, v114, v116, v114
	v_mul_f32_e32 v116, 0xbfcc422a, v116
	v_mul_f32_e32 v116, 0x3fb8aa3b, v116
	v_exp_f32_e32 v116, v116
	v_pk_fma_f32 v[164:165], v[38:39], v[176:177], v[164:165]
	v_lshlrev_b32_e32 v172, 16, v117
	v_and_b32_e32 v173, 0xffff0000, v117
	v_add_f32_e32 v116, 1.0, v116
	v_rcp_f32_e32 v118, v116
	v_mul_f32_e32 v116, 0x3d372713, v115
	v_mul_f32_e32 v116, v115, v116
	v_fma_f32 v116, v115, v116, v115
	v_mul_f32_e32 v116, 0xbfcc422a, v116
	v_mul_f32_e32 v116, 0x3fb8aa3b, v116
	v_exp_f32_e32 v116, v116
	v_pk_fma_f32 v[190:191], v[6:7], v[190:191], v[46:47]
	v_pk_fma_f32 v[184:185], v[8:9], v[184:185], v[48:49]
	v_pk_fma_f32 v[190:191], v[14:15], v[200:201], v[190:191]
	v_add_f32_e32 v116, 1.0, v116
	v_rcp_f32_e32 v119, v116
	v_pk_fma_f32 v[184:185], v[16:17], v[198:199], v[184:185]
	v_pk_fma_f32 v[170:171], v[18:19], v[188:189], v[170:171]
	v_pk_fma_f32 v[168:169], v[146:147], v[168:169], v[140:141]
	v_pk_mul_f32 v[114:115], v[114:115], v[118:119]
	v_pk_fma_f32 v[168:169], v[20:21], v[178:179], v[168:169]
	v_pk_mul_f32 v[194:195], v[164:165], v[114:115]
	v_lshlrev_b32_e32 v164, 16, v121
	v_and_b32_e32 v165, 0xffff0000, v121
	global_load_dwordx4 v[114:117], v[130:131], off nt
	v_pk_fma_f32 v[130:131], v[4:5], v[186:187], v[44:45]
	global_load_dwordx4 v[118:121], v[132:133], off nt
	v_pk_fma_f32 v[162:163], v[40:41], v[164:165], v[162:163]
	v_pk_fma_f32 v[130:131], v[12:13], v[180:181], v[130:131]
	v_pk_fma_f32 v[182:183], v[2:3], v[182:183], v[42:43]
	v_pk_fma_f32 v[130:131], v[28:29], v[172:173], v[130:131]
	v_pk_fma_f32 v[182:183], v[10:11], v[192:193], v[182:183]
	v_mul_f32_e32 v132, 0x3d372713, v130
	v_mul_f32_e32 v133, 0x3d372713, v131
	v_mul_f32_e32 v132, v130, v132
	v_mul_f32_e32 v133, v131, v133
	v_fma_f32 v132, v130, v132, v130
	v_fma_f32 v133, v131, v133, v131
	v_mul_f32_e32 v132, 0xbfcc422a, v132
	v_mul_f32_e32 v133, 0xbfcc422a, v133
	v_mul_f32_e32 v132, 0x3fb8aa3b, v132
	v_mul_f32_e32 v133, 0x3fb8aa3b, v133
	v_exp_f32_e32 v132, v132
	v_exp_f32_e32 v133, v133
	v_pk_fma_f32 v[166:167], v[148:149], v[166:167], v[142:143]
	v_pk_fma_f32 v[160:161], v[24:25], v[164:165], v[160:161]
	v_add_f32_e32 v132, 1.0, v132
	v_add_f32_e32 v133, 1.0, v133
	v_rcp_f32_e32 v132, v132
	v_rcp_f32_e32 v133, v133
	v_pk_fma_f32 v[166:167], v[22:23], v[176:177], v[166:167]
	v_pk_mul_f32 v[130:131], v[130:131], v[132:133]
	s_nop 0
	v_pk_mul_f32 v[162:163], v[162:163], v[130:131]
	v_cvt_pk_bf16_f32 v130, v202, v203
	v_cvt_pk_bf16_f32 v133, v162, v163
	v_add_u32_e32 v162, -1, v135
	v_cvt_pk_bf16_f32 v131, v196, v197
	v_cvt_pk_bf16_f32 v132, v194, v195
	v_mad_i64_i32 v[162:163], s[0:1], v162, s17, v[154:155]
	global_store_dwordx4 v[162:163], v[130:133], off nt
	s_waitcnt vmcnt(25)
	s_nop 0
	v_lshlrev_b32_e32 v162, 16, v122
	v_and_b32_e32 v163, 0xffff0000, v122
	v_pk_fma_f32 v[190:191], v[30:31], v[162:163], v[190:191]
	v_or_b32_e32 v130, 7, v175
	v_mul_f32_e32 v122, 0x3d372713, v190
	v_mul_f32_e32 v122, v190, v122
	v_fma_f32 v122, v190, v122, v190
	v_mul_f32_e32 v122, 0xbfcc422a, v122
	v_mul_f32_e32 v122, 0x3fb8aa3b, v122
	v_exp_f32_e32 v122, v122
	v_lshlrev_b32_e32 v186, 16, v126
	v_and_b32_e32 v187, 0xffff0000, v126
	v_pk_fma_f32 v[170:171], v[34:35], v[186:187], v[170:171]
	v_add_f32_e32 v122, 1.0, v122
	v_rcp_f32_e32 v194, v122
	v_mul_f32_e32 v122, 0x3d372713, v191
	v_mul_f32_e32 v122, v191, v122
	v_fma_f32 v122, v191, v122, v191
	v_mul_f32_e32 v122, 0xbfcc422a, v122
	v_mul_f32_e32 v122, 0x3fb8aa3b, v122
	v_exp_f32_e32 v122, v122
	v_lshlrev_b32_e32 v126, 16, v127
	v_and_b32_e32 v127, 0xffff0000, v127
	v_pk_fma_f32 v[168:169], v[36:37], v[126:127], v[168:169]
	v_add_f32_e32 v122, 1.0, v122
	v_rcp_f32_e32 v195, v122
	v_lshlrev_b32_e32 v122, 16, v123
	v_and_b32_e32 v123, 0xffff0000, v123
	v_pk_fma_f32 v[184:185], v[32:33], v[122:123], v[184:185]
	v_pk_mul_f32 v[188:189], v[190:191], v[194:195]
	v_mul_f32_e32 v175, 0x3d372713, v184
	v_mul_f32_e32 v175, v184, v175
	v_fma_f32 v175, v184, v175, v184
	v_mul_f32_e32 v175, 0xbfcc422a, v175
	v_mul_f32_e32 v175, 0x3fb8aa3b, v175
	v_exp_f32_e32 v175, v175
	v_pk_mul_f32 v[170:171], v[170:171], v[188:189]
	v_mad_i64_i32 v[130:131], s[0:1], v130, s15, v[152:153]
	v_add_f32_e32 v175, 1.0, v175
	v_rcp_f32_e32 v188, v175
	v_mul_f32_e32 v175, 0x3d372713, v185
	v_mul_f32_e32 v175, v185, v175
	v_fma_f32 v175, v185, v175, v185
	v_mul_f32_e32 v175, 0xbfcc422a, v175
	v_mul_f32_e32 v175, 0x3fb8aa3b, v175
	v_exp_f32_e32 v175, v175
	v_lshl_add_u64 v[132:133], v[130:131], 0, s[8:9]
	v_add_f32_e32 v175, 1.0, v175
	v_rcp_f32_e32 v189, v175
	s_nop 0
	v_pk_mul_f32 v[178:179], v[184:185], v[188:189]
	s_nop 0
	v_pk_mul_f32 v[168:169], v[168:169], v[178:179]
	v_lshlrev_b32_e32 v178, 16, v124
	v_and_b32_e32 v179, 0xffff0000, v124
	v_pk_fma_f32 v[182:183], v[26:27], v[178:179], v[182:183]
	v_lshlrev_b32_e32 v184, 16, v128
	v_mul_f32_e32 v124, 0x3d372713, v182
	v_mul_f32_e32 v124, v182, v124
	v_fma_f32 v124, v182, v124, v182
	v_mul_f32_e32 v124, 0xbfcc422a, v124
	v_mul_f32_e32 v124, 0x3fb8aa3b, v124
	v_exp_f32_e32 v124, v124
	v_and_b32_e32 v185, 0xffff0000, v128
	v_pk_fma_f32 v[166:167], v[38:39], v[184:185], v[166:167]
	v_add_f32_e32 v124, 1.0, v124
	v_rcp_f32_e32 v188, v124
	v_mul_f32_e32 v124, 0x3d372713, v183
	v_mul_f32_e32 v124, v183, v124
	v_fma_f32 v124, v183, v124, v183
	v_mul_f32_e32 v124, 0xbfcc422a, v124
	v_mul_f32_e32 v124, 0x3fb8aa3b, v124
	v_exp_f32_e32 v124, v124
	s_nop 0
	v_add_f32_e32 v124, 1.0, v124
	v_rcp_f32_e32 v189, v124
	s_nop 0
	v_pk_mul_f32 v[176:177], v[182:183], v[188:189]
	s_nop 0
	v_pk_mul_f32 v[166:167], v[166:167], v[176:177]
	v_lshlrev_b32_e32 v176, 16, v125
	v_and_b32_e32 v177, 0xffff0000, v125
	v_lshlrev_b32_e32 v182, 16, v129
	v_and_b32_e32 v183, 0xffff0000, v129
	global_load_dwordx4 v[122:125], v[130:131], off nt
	v_pk_fma_f32 v[130:131], v[4:5], v[180:181], v[44:45]
	global_load_dwordx4 v[126:129], v[132:133], off nt
	v_pk_fma_f32 v[160:161], v[40:41], v[182:183], v[160:161]
	v_pk_fma_f32 v[130:131], v[12:13], v[172:173], v[130:131]
	s_nop 0
	v_pk_fma_f32 v[130:131], v[28:29], v[176:177], v[130:131]
	s_nop 0
	v_mul_f32_e32 v132, 0x3d372713, v130
	v_mul_f32_e32 v133, 0x3d372713, v131
	v_mul_f32_e32 v132, v130, v132
	v_mul_f32_e32 v133, v131, v133
	v_fma_f32 v132, v130, v132, v130
	v_fma_f32 v133, v131, v133, v131
	v_mul_f32_e32 v132, 0xbfcc422a, v132
	v_mul_f32_e32 v133, 0xbfcc422a, v133
	v_mul_f32_e32 v132, 0x3fb8aa3b, v132
	v_mul_f32_e32 v133, 0x3fb8aa3b, v133
	v_exp_f32_e32 v132, v132
	v_exp_f32_e32 v133, v133
	v_add_f32_e32 v132, 1.0, v132
	v_add_f32_e32 v133, 1.0, v133
	v_rcp_f32_e32 v132, v132
	v_rcp_f32_e32 v133, v133
	s_nop 0
	v_pk_mul_f32 v[130:131], v[130:131], v[132:133]
	s_nop 0
	v_pk_mul_f32 v[160:161], v[160:161], v[130:131]
	v_cvt_pk_bf16_f32 v130, v170, v171
	v_cvt_pk_bf16_f32 v131, v168, v169
	v_cvt_pk_bf16_f32 v132, v166, v167
	v_cvt_pk_bf16_f32 v133, v160, v161
	v_mad_i64_i32 v[160:161], s[0:1], v135, s17, v[154:155]
	v_mov_b32_e32 v135, v158
	global_store_dwordx4 v[160:161], v[130:133], off nt
	s_andn2_b64 exec, exec, s[12:13]
	s_cbranch_execnz .LBB0_859
	s_or_b64 exec, exec, s[12:13]

.LBB0_863:
	v_add_u32_e32 v123, 0x2000, v116
	v_mad_i64_i32 v[50:51], s[22:23], v123, s3, v[152:153]
	global_load_dwordx4 v[106:109], v[50:51], off
	v_add_co_u32_e32 v50, vcc, 0x5000, v50
	v_add_u32_e32 v135, 0x2001, v116
	s_nop 0
	v_addc_co_u32_e32 v51, vcc, 0, v51, vcc
	global_load_dwordx4 v[110:113], v[50:51], off offset:1536
	v_mad_i64_i32 v[50:51], s[22:23], v135, s3, v[152:153]
	global_load_dwordx4 v[98:101], v[50:51], off
	v_add_co_u32_e32 v50, vcc, s15, v50
	v_add_u32_e32 v122, 0x2002, v116
	s_nop 0
	v_addc_co_u32_e32 v51, vcc, 0, v51, vcc
	global_load_dwordx4 v[102:105], v[50:51], off offset:1536
	v_mad_i64_i32 v[50:51], s[22:23], v122, s3, v[152:153]
	global_load_dwordx4 v[90:93], v[50:51], off
	v_add_co_u32_e32 v50, vcc, s15, v50
	v_add_u32_e32 v121, 0x2003, v116
	s_nop 0
	v_addc_co_u32_e32 v51, vcc, 0, v51, vcc
	global_load_dwordx4 v[94:97], v[50:51], off offset:1536
	v_mad_i64_i32 v[50:51], s[22:23], v121, s3, v[152:153]
	global_load_dwordx4 v[82:85], v[50:51], off
	v_add_co_u32_e32 v50, vcc, s15, v50
	v_add_u32_e32 v120, 0x2004, v116
	s_nop 0
	v_addc_co_u32_e32 v51, vcc, 0, v51, vcc
	global_load_dwordx4 v[86:89], v[50:51], off offset:1536
	v_mad_i64_i32 v[50:51], s[22:23], v120, s3, v[152:153]
	global_load_dwordx4 v[74:77], v[50:51], off
	v_add_co_u32_e32 v50, vcc, s15, v50
	v_add_u32_e32 v119, 0x2005, v116
	s_nop 0
	v_addc_co_u32_e32 v51, vcc, 0, v51, vcc
	global_load_dwordx4 v[78:81], v[50:51], off offset:1536
	v_mad_i64_i32 v[50:51], s[22:23], v119, s3, v[152:153]
	global_load_dwordx4 v[66:69], v[50:51], off
	v_add_co_u32_e32 v50, vcc, s15, v50
	v_add_u32_e32 v118, 0x2006, v116
	s_nop 0
	v_addc_co_u32_e32 v51, vcc, 0, v51, vcc
	global_load_dwordx4 v[70:73], v[50:51], off offset:1536
	v_mad_i64_i32 v[50:51], s[22:23], v118, s3, v[152:153]
	global_load_dwordx4 v[58:61], v[50:51], off
	v_add_co_u32_e32 v50, vcc, s15, v50
	v_add_u32_e32 v117, 0x2007, v116
	s_nop 0
	v_addc_co_u32_e32 v51, vcc, 0, v51, vcc
	v_mad_i64_i32 v[54:55], s[22:23], v117, s3, v[152:153]
	global_load_dwordx4 v[62:65], v[50:51], off offset:1536
	v_ashrrev_i32_e32 v124, 3, v116
	global_load_dwordx4 v[50:53], v[54:55], off
	v_add_co_u32_e32 v54, vcc, s15, v54
	v_mad_i64_i32 v[132:133], s[22:23], v124, s16, v[114:115]
	s_nop 0
	v_addc_co_u32_e32 v55, vcc, 0, v55, vcc
	global_load_dwordx4 v[54:57], v[54:55], off offset:1536
	s_nop 0
	global_load_dwordx4 v[124:127], v[132:133], off offset:16
	global_load_dwordx4 v[128:131], v[132:133], off
	v_add_co_u32_e32 v156, vcc, s17, v132
	v_lshl_add_u64 v[160:161], v[132:133], 0, s[8:9]
	s_nop 0
	v_addc_co_u32_e32 v157, vcc, 0, v133, vcc
	global_load_dwordx4 v[156:159], v[156:157], off offset:2048
	s_nop 0
	global_load_dwordx4 v[160:163], v[160:161], off offset:16
	v_add_co_u32_e32 v164, vcc, s18, v132
	v_lshl_add_u64 v[168:169], v[132:133], 0, s[10:11]
	s_nop 0
	v_addc_co_u32_e32 v165, vcc, 0, v133, vcc
	v_lshl_add_u64 v[172:173], v[132:133], 0, s[12:13]
	v_add_co_u32_e32 v132, vcc, s19, v132
	global_load_dwordx4 v[164:167], v[164:165], off offset:3072
	s_nop 0
	global_load_dwordx4 v[168:171], v[168:169], off offset:16
	v_addc_co_u32_e32 v133, vcc, 0, v133, vcc
	global_load_dwordx4 v[176:179], v[132:133], off offset:1024
	global_load_dwordx4 v[180:183], v[172:173], off offset:16
	s_waitcnt vmcnt(0)
	v_lshlrev_b32_e32 v132, 16, v106
	v_and_b32_e32 v133, 0xffff0000, v106
	v_lshlrev_b32_e32 v172, 16, v110
	v_and_b32_e32 v173, 0xffff0000, v110
	v_lshlrev_b32_e32 v110, 16, v111
	v_and_b32_e32 v111, 0xffff0000, v111
	v_add_u32_e32 v1, s14, v1
	v_cmp_lt_i32_e32 vcc, s21, v1
	v_add_u32_e32 v116, s2, v116
	s_or_b64 s[0:1], vcc, s[0:1]
	v_pk_fma_f32 v[128:129], v[6:7], v[128:129], v[46:47]
	s_nop 0
	v_pk_fma_f32 v[128:129], v[14:15], v[156:157], v[128:129]
	s_nop 0
	v_pk_fma_f32 v[128:129], v[30:31], v[132:133], v[128:129]
	v_pk_fma_f32 v[164:165], v[138:139], v[164:165], v[136:137]
	v_mul_f32_e32 v106, 0x3d372713, v128
	v_mul_f32_e32 v106, v128, v106
	v_fma_f32 v106, v128, v106, v128
	v_mul_f32_e32 v106, 0xbfcc422a, v106
	v_mul_f32_e32 v106, 0x3fb8aa3b, v106
	v_exp_f32_e32 v106, v106
	v_pk_fma_f32 v[164:165], v[18:19], v[176:177], v[164:165]
	v_pk_fma_f32 v[166:167], v[146:147], v[166:167], v[140:141]
	v_pk_fma_f32 v[164:165], v[34:35], v[172:173], v[164:165]
	v_add_f32_e32 v106, 1.0, v106
	v_rcp_f32_e32 v184, v106
	v_mul_f32_e32 v106, 0x3d372713, v129
	v_mul_f32_e32 v106, v129, v106
	v_fma_f32 v106, v129, v106, v129
	v_mul_f32_e32 v106, 0xbfcc422a, v106
	v_mul_f32_e32 v106, 0x3fb8aa3b, v106
	v_exp_f32_e32 v106, v106
	v_pk_fma_f32 v[166:167], v[20:21], v[178:179], v[166:167]
	v_pk_fma_f32 v[168:169], v[148:149], v[168:169], v[142:143]
	v_pk_fma_f32 v[166:167], v[36:37], v[110:111], v[166:167]
	v_add_f32_e32 v106, 1.0, v106
	v_rcp_f32_e32 v185, v106
	v_pk_fma_f32 v[168:169], v[22:23], v[180:181], v[168:169]
	v_pk_mul_f32 v[128:129], v[128:129], v[184:185]
	s_nop 0
	v_pk_mul_f32 v[128:129], v[164:165], v[128:129]
	v_lshlrev_b32_e32 v164, 16, v107
	v_and_b32_e32 v165, 0xffff0000, v107
	v_pk_fma_f32 v[106:107], v[8:9], v[130:131], v[48:49]
	v_lshlrev_b32_e32 v184, 16, v112
	v_pk_fma_f32 v[106:107], v[16:17], v[158:159], v[106:107]
	v_and_b32_e32 v185, 0xffff0000, v112
	v_pk_fma_f32 v[106:107], v[32:33], v[164:165], v[106:107]
	v_pk_fma_f32 v[168:169], v[38:39], v[184:185], v[168:169]
	v_mul_f32_e32 v130, 0x3d372713, v106
	v_mul_f32_e32 v131, 0x3d372713, v107
	v_mul_f32_e32 v130, v106, v130
	v_mul_f32_e32 v131, v107, v131
	v_fma_f32 v130, v106, v130, v106
	v_fma_f32 v131, v107, v131, v107
	v_mul_f32_e32 v130, 0xbfcc422a, v130
	v_mul_f32_e32 v131, 0xbfcc422a, v131
	v_mul_f32_e32 v130, 0x3fb8aa3b, v130
	v_mul_f32_e32 v131, 0x3fb8aa3b, v131
	v_exp_f32_e32 v130, v130
	v_exp_f32_e32 v131, v131
	v_lshlrev_b32_e32 v112, 16, v113
	v_and_b32_e32 v113, 0xffff0000, v113
	v_add_f32_e32 v130, 1.0, v130
	v_add_f32_e32 v131, 1.0, v131
	v_rcp_f32_e32 v130, v130
	v_rcp_f32_e32 v131, v131
	s_nop 0
	v_pk_mul_f32 v[106:107], v[106:107], v[130:131]
	s_nop 0
	v_pk_mul_f32 v[130:131], v[166:167], v[106:107]
	v_pk_fma_f32 v[106:107], v[2:3], v[124:125], v[42:43]
	v_lshlrev_b32_e32 v166, 16, v108
	v_and_b32_e32 v167, 0xffff0000, v108
	v_pk_fma_f32 v[106:107], v[10:11], v[160:161], v[106:107]
	s_nop 0
	v_pk_fma_f32 v[106:107], v[26:27], v[166:167], v[106:107]
	s_nop 0
	v_mul_f32_e32 v108, 0x3d372713, v106
	v_mul_f32_e32 v108, v106, v108
	v_fma_f32 v108, v106, v108, v106
	v_mul_f32_e32 v108, 0xbfcc422a, v108
	v_mul_f32_e32 v108, 0x3fb8aa3b, v108
	v_exp_f32_e32 v108, v108
	s_nop 0
	v_add_f32_e32 v108, 1.0, v108
	v_rcp_f32_e32 v124, v108
	v_mul_f32_e32 v108, 0x3d372713, v107
	v_mul_f32_e32 v108, v107, v108
	v_fma_f32 v108, v107, v108, v107
	v_mul_f32_e32 v108, 0xbfcc422a, v108
	v_mul_f32_e32 v108, 0x3fb8aa3b, v108
	v_exp_f32_e32 v108, v108
	s_nop 0
	v_add_f32_e32 v108, 1.0, v108
	v_rcp_f32_e32 v125, v108
	s_nop 0
	v_pk_mul_f32 v[106:107], v[106:107], v[124:125]
	s_nop 0
	v_pk_mul_f32 v[124:125], v[168:169], v[106:107]
	v_pk_fma_f32 v[106:107], v[4:5], v[126:127], v[44:45]
	v_lshlrev_b32_e32 v168, 16, v109
	v_and_b32_e32 v169, 0xffff0000, v109
	v_pk_fma_f32 v[106:107], v[12:13], v[162:163], v[106:107]
	v_pk_fma_f32 v[126:127], v[150:151], v[170:171], v[144:145]
	v_pk_fma_f32 v[106:107], v[28:29], v[168:169], v[106:107]
	v_pk_fma_f32 v[126:127], v[24:25], v[182:183], v[126:127]
	v_mul_f32_e32 v108, 0x3d372713, v106
	v_mul_f32_e32 v109, 0x3d372713, v107
	v_mul_f32_e32 v108, v106, v108
	v_mul_f32_e32 v109, v107, v109
	v_fma_f32 v108, v106, v108, v106
	v_fma_f32 v109, v107, v109, v107
	v_mul_f32_e32 v108, 0xbfcc422a, v108
	v_mul_f32_e32 v109, 0xbfcc422a, v109
	v_mul_f32_e32 v108, 0x3fb8aa3b, v108
	v_mul_f32_e32 v109, 0x3fb8aa3b, v109
	v_exp_f32_e32 v108, v108
	v_exp_f32_e32 v109, v109
	v_pk_fma_f32 v[126:127], v[40:41], v[112:113], v[126:127]
	v_add_f32_e32 v108, 1.0, v108
	v_add_f32_e32 v109, 1.0, v109
	v_rcp_f32_e32 v108, v108
	v_rcp_f32_e32 v109, v109
	s_nop 0
	v_pk_mul_f32 v[106:107], v[106:107], v[108:109]
	s_nop 0
	v_pk_mul_f32 v[126:127], v[126:127], v[106:107]
	v_cvt_pk_bf16_f32 v106, v128, v129
	v_cvt_pk_bf16_f32 v107, v130, v131
	v_cvt_pk_bf16_f32 v108, v124, v125
	v_cvt_pk_bf16_f32 v109, v126, v127
	v_mad_i64_i32 v[124:125], s[22:23], v123, s20, v[154:155]
	global_store_dwordx4 v[124:125], v[106:109], off nt
	v_pk_fma_f32 v[124:125], v[6:7], v[156:157], v[46:47]
	v_pk_fma_f32 v[128:129], v[138:139], v[176:177], v[136:137]
	v_lshlrev_b32_e32 v106, 16, v98
	v_and_b32_e32 v107, 0xffff0000, v98
	v_pk_fma_f32 v[124:125], v[14:15], v[132:133], v[124:125]
	v_lshlrev_b32_e32 v108, 16, v102
	v_pk_fma_f32 v[124:125], v[30:31], v[106:107], v[124:125]
	v_and_b32_e32 v109, 0xffff0000, v102
	v_mul_f32_e32 v98, 0x3d372713, v124
	v_mul_f32_e32 v98, v124, v98
	v_fma_f32 v98, v124, v98, v124
	v_mul_f32_e32 v98, 0xbfcc422a, v98
	v_mul_f32_e32 v98, 0x3fb8aa3b, v98
	v_exp_f32_e32 v98, v98
	v_pk_fma_f32 v[128:129], v[18:19], v[172:173], v[128:129]
	v_pk_fma_f32 v[130:131], v[146:147], v[178:179], v[140:141]
	v_pk_fma_f32 v[128:129], v[34:35], v[108:109], v[128:129]
	v_add_f32_e32 v98, 1.0, v98
	v_rcp_f32_e32 v126, v98
	v_mul_f32_e32 v98, 0x3d372713, v125
	v_mul_f32_e32 v98, v125, v98
	v_fma_f32 v98, v125, v98, v125
	v_mul_f32_e32 v98, 0xbfcc422a, v98
	v_mul_f32_e32 v98, 0x3fb8aa3b, v98
	v_exp_f32_e32 v98, v98
	v_lshlrev_b32_e32 v102, 16, v103
	v_and_b32_e32 v103, 0xffff0000, v103
	v_pk_fma_f32 v[130:131], v[20:21], v[110:111], v[130:131]
	v_add_f32_e32 v98, 1.0, v98
	v_rcp_f32_e32 v127, v98
	v_pk_fma_f32 v[130:131], v[36:37], v[102:103], v[130:131]
	v_lshlrev_b32_e32 v156, 16, v104
	v_and_b32_e32 v157, 0xffff0000, v104
	v_pk_mul_f32 v[124:125], v[124:125], v[126:127]
	v_lshlrev_b32_e32 v126, 16, v99
	v_and_b32_e32 v127, 0xffff0000, v99
	v_pk_fma_f32 v[98:99], v[8:9], v[158:159], v[48:49]
	v_pk_mul_f32 v[124:125], v[128:129], v[124:125]
	v_pk_fma_f32 v[98:99], v[16:17], v[164:165], v[98:99]
	v_lshlrev_b32_e32 v104, 16, v105
	v_pk_fma_f32 v[98:99], v[32:33], v[126:127], v[98:99]
	v_and_b32_e32 v105, 0xffff0000, v105
	v_mul_f32_e32 v123, 0x3d372713, v98
	v_mul_f32_e32 v123, v98, v123
	v_fma_f32 v123, v98, v123, v98
	v_mul_f32_e32 v123, 0xbfcc422a, v123
	v_mul_f32_e32 v123, 0x3fb8aa3b, v123
	v_exp_f32_e32 v123, v123
	v_pk_fma_f32 v[110:111], v[146:147], v[110:111], v[140:141]
	v_add_f32_e32 v123, 1.0, v123
	v_rcp_f32_e32 v128, v123
	v_mul_f32_e32 v123, 0x3d372713, v99
	v_mul_f32_e32 v123, v99, v123
	v_fma_f32 v123, v99, v123, v99
	v_mul_f32_e32 v123, 0xbfcc422a, v123
	v_mul_f32_e32 v123, 0x3fb8aa3b, v123
	v_exp_f32_e32 v123, v123
	v_pk_fma_f32 v[110:111], v[20:21], v[102:103], v[110:111]
	v_pk_fma_f32 v[102:103], v[146:147], v[102:103], v[140:141]
	v_add_f32_e32 v123, 1.0, v123
	v_rcp_f32_e32 v129, v123
	s_nop 0
	v_pk_mul_f32 v[98:99], v[98:99], v[128:129]
	s_nop 0
	v_pk_mul_f32 v[128:129], v[130:131], v[98:99]
	v_pk_fma_f32 v[98:99], v[2:3], v[160:161], v[42:43]
	v_lshlrev_b32_e32 v130, 16, v100
	v_and_b32_e32 v131, 0xffff0000, v100
	v_pk_fma_f32 v[98:99], v[10:11], v[166:167], v[98:99]
	v_pk_fma_f32 v[160:161], v[148:149], v[180:181], v[142:143]
	v_pk_fma_f32 v[98:99], v[26:27], v[130:131], v[98:99]
	v_pk_fma_f32 v[160:161], v[22:23], v[184:185], v[160:161]
	v_mul_f32_e32 v100, 0x3d372713, v98
	v_mul_f32_e32 v100, v98, v100
	v_fma_f32 v100, v98, v100, v98
	v_mul_f32_e32 v100, 0xbfcc422a, v100
	v_mul_f32_e32 v100, 0x3fb8aa3b, v100
	v_exp_f32_e32 v100, v100
	v_pk_fma_f32 v[160:161], v[38:39], v[156:157], v[160:161]
	v_add_f32_e32 v100, 1.0, v100
	v_rcp_f32_e32 v158, v100
	v_mul_f32_e32 v100, 0x3d372713, v99
	v_mul_f32_e32 v100, v99, v100
	v_fma_f32 v100, v99, v100, v99
	v_mul_f32_e32 v100, 0xbfcc422a, v100
	v_mul_f32_e32 v100, 0x3fb8aa3b, v100
	v_exp_f32_e32 v100, v100
	s_nop 0
	v_add_f32_e32 v100, 1.0, v100
	v_rcp_f32_e32 v159, v100
	s_nop 0
	v_pk_mul_f32 v[98:99], v[98:99], v[158:159]
	s_nop 0
	v_pk_mul_f32 v[158:159], v[160:161], v[98:99]
	v_pk_fma_f32 v[98:99], v[4:5], v[162:163], v[44:45]
	v_lshlrev_b32_e32 v160, 16, v101
	v_and_b32_e32 v161, 0xffff0000, v101
	v_pk_fma_f32 v[98:99], v[12:13], v[168:169], v[98:99]
	v_pk_fma_f32 v[162:163], v[150:151], v[182:183], v[144:145]
	v_pk_fma_f32 v[98:99], v[28:29], v[160:161], v[98:99]
	v_pk_fma_f32 v[162:163], v[24:25], v[112:113], v[162:163]
	v_mul_f32_e32 v100, 0x3d372713, v98
	v_mul_f32_e32 v101, 0x3d372713, v99
	v_mul_f32_e32 v100, v98, v100
	v_mul_f32_e32 v101, v99, v101
	v_fma_f32 v100, v98, v100, v98
	v_fma_f32 v101, v99, v101, v99
	v_mul_f32_e32 v100, 0xbfcc422a, v100
	v_mul_f32_e32 v101, 0xbfcc422a, v101
	v_mul_f32_e32 v100, 0x3fb8aa3b, v100
	v_mul_f32_e32 v101, 0x3fb8aa3b, v101
	v_exp_f32_e32 v100, v100
	v_exp_f32_e32 v101, v101
	v_pk_fma_f32 v[162:163], v[40:41], v[104:105], v[162:163]
	v_pk_fma_f32 v[112:113], v[150:151], v[112:113], v[144:145]
	v_add_f32_e32 v100, 1.0, v100
	v_add_f32_e32 v101, 1.0, v101
	v_rcp_f32_e32 v100, v100
	v_rcp_f32_e32 v101, v101
	v_pk_fma_f32 v[112:113], v[24:25], v[104:105], v[112:113]
	v_pk_fma_f32 v[104:105], v[150:151], v[104:105], v[144:145]
	v_pk_mul_f32 v[98:99], v[98:99], v[100:101]
	s_nop 0
	v_pk_mul_f32 v[162:163], v[162:163], v[98:99]
	v_cvt_pk_bf16_f32 v98, v124, v125
	v_cvt_pk_bf16_f32 v99, v128, v129
	v_cvt_pk_bf16_f32 v100, v158, v159
	v_cvt_pk_bf16_f32 v101, v162, v163
	v_mad_i64_i32 v[124:125], s[22:23], v135, s20, v[154:155]
	global_store_dwordx4 v[124:125], v[98:101], off nt
	v_pk_fma_f32 v[124:125], v[6:7], v[132:133], v[46:47]
	v_pk_fma_f32 v[132:133], v[138:139], v[172:173], v[136:137]
	v_lshlrev_b32_e32 v98, 16, v90
	v_and_b32_e32 v99, 0xffff0000, v90
	v_pk_fma_f32 v[124:125], v[14:15], v[106:107], v[124:125]
	v_lshlrev_b32_e32 v100, 16, v94
	v_pk_fma_f32 v[124:125], v[30:31], v[98:99], v[124:125]
	v_and_b32_e32 v101, 0xffff0000, v94
	v_mul_f32_e32 v90, 0x3d372713, v124
	v_mul_f32_e32 v90, v124, v90
	v_fma_f32 v90, v124, v90, v124
	v_mul_f32_e32 v90, 0xbfcc422a, v90
	v_mul_f32_e32 v90, 0x3fb8aa3b, v90
	v_exp_f32_e32 v90, v90
	v_pk_fma_f32 v[132:133], v[18:19], v[108:109], v[132:133]
	v_lshlrev_b32_e32 v94, 16, v95
	v_pk_fma_f32 v[132:133], v[34:35], v[100:101], v[132:133]
	v_add_f32_e32 v90, 1.0, v90
	v_rcp_f32_e32 v128, v90
	v_mul_f32_e32 v90, 0x3d372713, v125
	v_mul_f32_e32 v90, v125, v90
	v_fma_f32 v90, v125, v90, v125
	v_mul_f32_e32 v90, 0xbfcc422a, v90
	v_mul_f32_e32 v90, 0x3fb8aa3b, v90
	v_exp_f32_e32 v90, v90
	v_and_b32_e32 v95, 0xffff0000, v95
	v_pk_fma_f32 v[110:111], v[36:37], v[94:95], v[110:111]
	v_lshlrev_b32_e32 v158, 16, v96
	v_add_f32_e32 v90, 1.0, v90
	v_rcp_f32_e32 v129, v90
	v_and_b32_e32 v159, 0xffff0000, v96
	v_lshlrev_b32_e32 v96, 16, v97
	v_and_b32_e32 v97, 0xffff0000, v97
	v_pk_mul_f32 v[124:125], v[124:125], v[128:129]
	v_lshlrev_b32_e32 v128, 16, v91
	v_and_b32_e32 v129, 0xffff0000, v91
	v_pk_fma_f32 v[90:91], v[8:9], v[164:165], v[48:49]
	v_pk_mul_f32 v[124:125], v[132:133], v[124:125]
	v_pk_fma_f32 v[90:91], v[16:17], v[126:127], v[90:91]
	v_pk_fma_f32 v[164:165], v[148:149], v[184:185], v[142:143]
	v_pk_fma_f32 v[90:91], v[32:33], v[128:129], v[90:91]
	v_pk_fma_f32 v[164:165], v[22:23], v[156:157], v[164:165]
	v_mul_f32_e32 v123, 0x3d372713, v90
	v_mul_f32_e32 v123, v90, v123
	v_fma_f32 v123, v90, v123, v90
	v_mul_f32_e32 v123, 0xbfcc422a, v123
	v_mul_f32_e32 v123, 0x3fb8aa3b, v123
	v_exp_f32_e32 v123, v123
	v_pk_fma_f32 v[164:165], v[38:39], v[158:159], v[164:165]
	v_pk_fma_f32 v[112:113], v[40:41], v[96:97], v[112:113]
	v_pk_fma_f32 v[106:107], v[6:7], v[106:107], v[46:47]
	v_add_f32_e32 v123, 1.0, v123
	v_rcp_f32_e32 v132, v123
	v_mul_f32_e32 v123, 0x3d372713, v91
	v_mul_f32_e32 v123, v91, v123
	v_fma_f32 v123, v91, v123, v91
	v_mul_f32_e32 v123, 0xbfcc422a, v123
	v_mul_f32_e32 v123, 0x3fb8aa3b, v123
	v_exp_f32_e32 v123, v123
	v_pk_fma_f32 v[106:107], v[14:15], v[98:99], v[106:107]
	v_pk_fma_f32 v[108:109], v[138:139], v[108:109], v[136:137]
	v_pk_fma_f32 v[102:103], v[20:21], v[94:95], v[102:103]
	v_add_f32_e32 v123, 1.0, v123
	v_rcp_f32_e32 v133, v123
	v_pk_fma_f32 v[108:109], v[18:19], v[100:101], v[108:109]
	v_pk_fma_f32 v[104:105], v[24:25], v[96:97], v[104:105]
	v_pk_fma_f32 v[98:99], v[6:7], v[98:99], v[46:47]
	v_pk_mul_f32 v[90:91], v[90:91], v[132:133]
	v_lshlrev_b32_e32 v132, 16, v92
	v_pk_mul_f32 v[110:111], v[110:111], v[90:91]
	v_pk_fma_f32 v[90:91], v[2:3], v[166:167], v[42:43]
	v_and_b32_e32 v133, 0xffff0000, v92
	v_pk_fma_f32 v[90:91], v[10:11], v[130:131], v[90:91]
	v_pk_fma_f32 v[100:101], v[138:139], v[100:101], v[136:137]
	v_pk_fma_f32 v[90:91], v[26:27], v[132:133], v[90:91]
	v_pk_fma_f32 v[94:95], v[146:147], v[94:95], v[140:141]
	v_mul_f32_e32 v92, 0x3d372713, v90
	v_mul_f32_e32 v92, v90, v92
	v_fma_f32 v92, v90, v92, v90
	v_mul_f32_e32 v92, 0xbfcc422a, v92
	v_mul_f32_e32 v92, 0x3fb8aa3b, v92
	v_exp_f32_e32 v92, v92
	v_pk_fma_f32 v[96:97], v[150:151], v[96:97], v[144:145]
	v_add_f32_e32 v92, 1.0, v92
	v_rcp_f32_e32 v162, v92
	v_mul_f32_e32 v92, 0x3d372713, v91
	v_mul_f32_e32 v92, v91, v92
	v_fma_f32 v92, v91, v92, v91
	v_mul_f32_e32 v92, 0xbfcc422a, v92
	v_mul_f32_e32 v92, 0x3fb8aa3b, v92
	v_exp_f32_e32 v92, v92
	s_nop 0
	v_add_f32_e32 v92, 1.0, v92
	v_rcp_f32_e32 v163, v92
	s_nop 0
	v_pk_mul_f32 v[90:91], v[90:91], v[162:163]
	s_nop 0
	v_pk_mul_f32 v[162:163], v[164:165], v[90:91]
	v_pk_fma_f32 v[90:91], v[4:5], v[168:169], v[44:45]
	v_lshlrev_b32_e32 v164, 16, v93
	v_and_b32_e32 v165, 0xffff0000, v93
	v_pk_fma_f32 v[90:91], v[12:13], v[160:161], v[90:91]
	s_nop 0
	v_pk_fma_f32 v[90:91], v[28:29], v[164:165], v[90:91]
	s_nop 0
	v_mul_f32_e32 v92, 0x3d372713, v90
	v_mul_f32_e32 v93, 0x3d372713, v91
	v_mul_f32_e32 v92, v90, v92
	v_mul_f32_e32 v93, v91, v93
	v_fma_f32 v92, v90, v92, v90
	v_fma_f32 v93, v91, v93, v91
	v_mul_f32_e32 v92, 0xbfcc422a, v92
	v_mul_f32_e32 v93, 0xbfcc422a, v93
	v_mul_f32_e32 v92, 0x3fb8aa3b, v92
	v_mul_f32_e32 v93, 0x3fb8aa3b, v93
	v_exp_f32_e32 v92, v92
	v_exp_f32_e32 v93, v93
	v_add_f32_e32 v92, 1.0, v92
	v_add_f32_e32 v93, 1.0, v93
	v_rcp_f32_e32 v92, v92
	v_rcp_f32_e32 v93, v93
	s_nop 0
	v_pk_mul_f32 v[90:91], v[90:91], v[92:93]
	s_nop 0
	v_pk_mul_f32 v[112:113], v[112:113], v[90:91]
	v_cvt_pk_bf16_f32 v90, v124, v125
	v_cvt_pk_bf16_f32 v91, v110, v111
	v_cvt_pk_bf16_f32 v92, v162, v163
	v_cvt_pk_bf16_f32 v93, v112, v113
	v_mad_i64_i32 v[110:111], s[22:23], v122, s20, v[154:155]
	global_store_dwordx4 v[110:111], v[90:93], off nt
	v_pk_fma_f32 v[124:125], v[148:149], v[156:157], v[142:143]
	v_lshlrev_b32_e32 v112, 16, v88
	v_lshlrev_b32_e32 v90, 16, v82
	v_and_b32_e32 v91, 0xffff0000, v82
	v_pk_fma_f32 v[106:107], v[30:31], v[90:91], v[106:107]
	v_lshlrev_b32_e32 v92, 16, v86
	v_mul_f32_e32 v82, 0x3d372713, v106
	v_mul_f32_e32 v82, v106, v82
	v_fma_f32 v82, v106, v82, v106
	v_mul_f32_e32 v82, 0xbfcc422a, v82
	v_mul_f32_e32 v82, 0x3fb8aa3b, v82
	v_exp_f32_e32 v82, v82
	v_and_b32_e32 v93, 0xffff0000, v86
	v_pk_fma_f32 v[108:109], v[34:35], v[92:93], v[108:109]
	v_lshlrev_b32_e32 v86, 16, v87
	v_add_f32_e32 v82, 1.0, v82
	v_rcp_f32_e32 v110, v82
	v_mul_f32_e32 v82, 0x3d372713, v107
	v_mul_f32_e32 v82, v107, v82
	v_fma_f32 v82, v107, v82, v107
	v_mul_f32_e32 v82, 0xbfcc422a, v82
	v_mul_f32_e32 v82, 0x3fb8aa3b, v82
	v_exp_f32_e32 v82, v82
	v_and_b32_e32 v87, 0xffff0000, v87
	v_pk_fma_f32 v[102:103], v[36:37], v[86:87], v[102:103]
	v_and_b32_e32 v113, 0xffff0000, v88
	v_add_f32_e32 v82, 1.0, v82
	v_rcp_f32_e32 v111, v82
	v_pk_fma_f32 v[124:125], v[22:23], v[158:159], v[124:125]
	v_lshlrev_b32_e32 v88, 16, v89
	v_pk_fma_f32 v[124:125], v[38:39], v[112:113], v[124:125]
	v_pk_mul_f32 v[106:107], v[106:107], v[110:111]
	v_and_b32_e32 v89, 0xffff0000, v89
	v_pk_mul_f32 v[106:107], v[108:109], v[106:107]
	v_lshlrev_b32_e32 v108, 16, v83
	v_and_b32_e32 v109, 0xffff0000, v83
	v_pk_fma_f32 v[82:83], v[8:9], v[126:127], v[48:49]
	v_pk_fma_f32 v[104:105], v[40:41], v[88:89], v[104:105]
	v_pk_fma_f32 v[82:83], v[16:17], v[128:129], v[82:83]
	v_pk_fma_f32 v[98:99], v[14:15], v[90:91], v[98:99]
	v_pk_fma_f32 v[82:83], v[32:33], v[108:109], v[82:83]
	v_pk_fma_f32 v[100:101], v[18:19], v[92:93], v[100:101]
	v_mul_f32_e32 v110, 0x3d372713, v82
	v_mul_f32_e32 v111, 0x3d372713, v83
	v_mul_f32_e32 v110, v82, v110
	v_mul_f32_e32 v111, v83, v111
	v_fma_f32 v110, v82, v110, v82
	v_fma_f32 v111, v83, v111, v83
	v_mul_f32_e32 v110, 0xbfcc422a, v110
	v_mul_f32_e32 v111, 0xbfcc422a, v111
	v_mul_f32_e32 v110, 0x3fb8aa3b, v110
	v_mul_f32_e32 v111, 0x3fb8aa3b, v111
	v_exp_f32_e32 v110, v110
	v_exp_f32_e32 v111, v111
	v_pk_fma_f32 v[94:95], v[20:21], v[86:87], v[94:95]
	v_pk_fma_f32 v[96:97], v[24:25], v[88:89], v[96:97]
	v_add_f32_e32 v110, 1.0, v110
	v_add_f32_e32 v111, 1.0, v111
	v_rcp_f32_e32 v110, v110
	v_rcp_f32_e32 v111, v111
	v_pk_fma_f32 v[90:91], v[6:7], v[90:91], v[46:47]
	v_pk_fma_f32 v[92:93], v[138:139], v[92:93], v[136:137]
	v_pk_fma_f32 v[86:87], v[146:147], v[86:87], v[140:141]
	v_pk_mul_f32 v[82:83], v[82:83], v[110:111]
	v_lshlrev_b32_e32 v110, 16, v84
	v_pk_mul_f32 v[102:103], v[102:103], v[82:83]
	v_pk_fma_f32 v[82:83], v[2:3], v[130:131], v[42:43]
	v_and_b32_e32 v111, 0xffff0000, v84
	v_pk_fma_f32 v[82:83], v[10:11], v[132:133], v[82:83]
	v_pk_fma_f32 v[88:89], v[150:151], v[88:89], v[144:145]
	v_pk_fma_f32 v[82:83], v[26:27], v[110:111], v[82:83]
	s_nop 0
	v_mul_f32_e32 v84, 0x3d372713, v82
	v_mul_f32_e32 v84, v82, v84
	v_fma_f32 v84, v82, v84, v82
	v_mul_f32_e32 v84, 0xbfcc422a, v84
	v_mul_f32_e32 v84, 0x3fb8aa3b, v84
	v_exp_f32_e32 v84, v84
	s_nop 0
	v_add_f32_e32 v84, 1.0, v84
	v_rcp_f32_e32 v122, v84
	v_mul_f32_e32 v84, 0x3d372713, v83
	v_mul_f32_e32 v84, v83, v84
	v_fma_f32 v84, v83, v84, v83
	v_mul_f32_e32 v84, 0xbfcc422a, v84
	v_mul_f32_e32 v84, 0x3fb8aa3b, v84
	v_exp_f32_e32 v84, v84
	s_nop 0
	v_add_f32_e32 v84, 1.0, v84
	v_rcp_f32_e32 v123, v84
	s_nop 0
	v_pk_mul_f32 v[82:83], v[82:83], v[122:123]
	s_nop 0
	v_pk_mul_f32 v[122:123], v[124:125], v[82:83]
	v_pk_fma_f32 v[82:83], v[4:5], v[160:161], v[44:45]
	v_lshlrev_b32_e32 v124, 16, v85
	v_and_b32_e32 v125, 0xffff0000, v85
	v_pk_fma_f32 v[82:83], v[12:13], v[164:165], v[82:83]
	s_nop 0
	v_pk_fma_f32 v[82:83], v[28:29], v[124:125], v[82:83]
	s_nop 0
	v_mul_f32_e32 v84, 0x3d372713, v82
	v_mul_f32_e32 v85, 0x3d372713, v83
	v_mul_f32_e32 v84, v82, v84
	v_mul_f32_e32 v85, v83, v85
	v_fma_f32 v84, v82, v84, v82
	v_fma_f32 v85, v83, v85, v83
	v_mul_f32_e32 v84, 0xbfcc422a, v84
	v_mul_f32_e32 v85, 0xbfcc422a, v85
	v_mul_f32_e32 v84, 0x3fb8aa3b, v84
	v_mul_f32_e32 v85, 0x3fb8aa3b, v85
	v_exp_f32_e32 v84, v84
	v_exp_f32_e32 v85, v85
	v_add_f32_e32 v84, 1.0, v84
	v_add_f32_e32 v85, 1.0, v85
	v_rcp_f32_e32 v84, v84
	v_rcp_f32_e32 v85, v85
	s_nop 0
	v_pk_mul_f32 v[82:83], v[82:83], v[84:85]
	s_nop 0
	v_pk_mul_f32 v[104:105], v[104:105], v[82:83]
	v_cvt_pk_bf16_f32 v82, v106, v107
	v_cvt_pk_bf16_f32 v83, v102, v103
	v_cvt_pk_bf16_f32 v84, v122, v123
	v_cvt_pk_bf16_f32 v85, v104, v105
	v_mad_i64_i32 v[102:103], s[22:23], v121, s20, v[154:155]
	global_store_dwordx4 v[102:103], v[82:85], off nt
	v_pk_fma_f32 v[122:123], v[148:149], v[158:159], v[142:143]
	v_lshlrev_b32_e32 v104, 16, v80
	v_lshlrev_b32_e32 v82, 16, v74
	v_and_b32_e32 v83, 0xffff0000, v74
	v_pk_fma_f32 v[98:99], v[30:31], v[82:83], v[98:99]
	v_lshlrev_b32_e32 v84, 16, v78
	v_mul_f32_e32 v74, 0x3d372713, v98
	v_mul_f32_e32 v74, v98, v74
	v_fma_f32 v74, v98, v74, v98
	v_mul_f32_e32 v74, 0xbfcc422a, v74
	v_mul_f32_e32 v74, 0x3fb8aa3b, v74
	v_exp_f32_e32 v74, v74
	v_and_b32_e32 v85, 0xffff0000, v78
	v_pk_fma_f32 v[100:101], v[34:35], v[84:85], v[100:101]
	v_lshlrev_b32_e32 v78, 16, v79
	v_add_f32_e32 v74, 1.0, v74
	v_rcp_f32_e32 v102, v74
	v_mul_f32_e32 v74, 0x3d372713, v99
	v_mul_f32_e32 v74, v99, v74
	v_fma_f32 v74, v99, v74, v99
	v_mul_f32_e32 v74, 0xbfcc422a, v74
	v_mul_f32_e32 v74, 0x3fb8aa3b, v74
	v_exp_f32_e32 v74, v74
	v_and_b32_e32 v79, 0xffff0000, v79
	v_pk_fma_f32 v[94:95], v[36:37], v[78:79], v[94:95]
	v_and_b32_e32 v105, 0xffff0000, v80
	v_add_f32_e32 v74, 1.0, v74
	v_rcp_f32_e32 v103, v74
	v_pk_fma_f32 v[122:123], v[22:23], v[112:113], v[122:123]
	v_lshlrev_b32_e32 v80, 16, v81
	v_pk_fma_f32 v[122:123], v[38:39], v[104:105], v[122:123]
	v_pk_mul_f32 v[98:99], v[98:99], v[102:103]
	v_and_b32_e32 v81, 0xffff0000, v81
	v_pk_mul_f32 v[98:99], v[100:101], v[98:99]
	v_lshlrev_b32_e32 v100, 16, v75
	v_and_b32_e32 v101, 0xffff0000, v75
	v_pk_fma_f32 v[74:75], v[8:9], v[128:129], v[48:49]
	v_pk_fma_f32 v[96:97], v[40:41], v[80:81], v[96:97]
	v_pk_fma_f32 v[74:75], v[16:17], v[108:109], v[74:75]
	v_pk_fma_f32 v[90:91], v[14:15], v[82:83], v[90:91]
	v_pk_fma_f32 v[74:75], v[32:33], v[100:101], v[74:75]
	v_pk_fma_f32 v[92:93], v[18:19], v[84:85], v[92:93]
	v_mul_f32_e32 v102, 0x3d372713, v74
	v_mul_f32_e32 v103, 0x3d372713, v75
	v_mul_f32_e32 v102, v74, v102
	v_mul_f32_e32 v103, v75, v103
	v_fma_f32 v102, v74, v102, v74
	v_fma_f32 v103, v75, v103, v75
	v_mul_f32_e32 v102, 0xbfcc422a, v102
	v_mul_f32_e32 v103, 0xbfcc422a, v103
	v_mul_f32_e32 v102, 0x3fb8aa3b, v102
	v_mul_f32_e32 v103, 0x3fb8aa3b, v103
	v_exp_f32_e32 v102, v102
	v_exp_f32_e32 v103, v103
	v_pk_fma_f32 v[86:87], v[20:21], v[78:79], v[86:87]
	v_pk_fma_f32 v[88:89], v[24:25], v[80:81], v[88:89]
	v_add_f32_e32 v102, 1.0, v102
	v_add_f32_e32 v103, 1.0, v103
	v_rcp_f32_e32 v102, v102
	v_rcp_f32_e32 v103, v103
	v_pk_fma_f32 v[82:83], v[6:7], v[82:83], v[46:47]
	v_pk_fma_f32 v[84:85], v[138:139], v[84:85], v[136:137]
	v_pk_fma_f32 v[78:79], v[146:147], v[78:79], v[140:141]
	v_pk_mul_f32 v[74:75], v[74:75], v[102:103]
	v_lshlrev_b32_e32 v102, 16, v76
	v_pk_mul_f32 v[94:95], v[94:95], v[74:75]
	v_pk_fma_f32 v[74:75], v[2:3], v[132:133], v[42:43]
	v_and_b32_e32 v103, 0xffff0000, v76
	v_pk_fma_f32 v[74:75], v[10:11], v[110:111], v[74:75]
	v_pk_fma_f32 v[80:81], v[150:151], v[80:81], v[144:145]
	v_pk_fma_f32 v[74:75], v[26:27], v[102:103], v[74:75]
	s_nop 0
	v_mul_f32_e32 v76, 0x3d372713, v74
	v_mul_f32_e32 v76, v74, v76
	v_fma_f32 v76, v74, v76, v74
	v_mul_f32_e32 v76, 0xbfcc422a, v76
	v_mul_f32_e32 v76, 0x3fb8aa3b, v76
	v_exp_f32_e32 v76, v76
	s_nop 0
	v_add_f32_e32 v76, 1.0, v76
	v_rcp_f32_e32 v106, v76
	v_mul_f32_e32 v76, 0x3d372713, v75
	v_mul_f32_e32 v76, v75, v76
	v_fma_f32 v76, v75, v76, v75
	v_mul_f32_e32 v76, 0xbfcc422a, v76
	v_mul_f32_e32 v76, 0x3fb8aa3b, v76
	v_exp_f32_e32 v76, v76
	s_nop 0
	v_add_f32_e32 v76, 1.0, v76
	v_rcp_f32_e32 v107, v76
	s_nop 0
	v_pk_mul_f32 v[74:75], v[74:75], v[106:107]
	s_nop 0
	v_pk_mul_f32 v[106:107], v[122:123], v[74:75]
	v_pk_fma_f32 v[74:75], v[4:5], v[164:165], v[44:45]
	v_lshlrev_b32_e32 v122, 16, v77
	v_and_b32_e32 v123, 0xffff0000, v77
	v_pk_fma_f32 v[74:75], v[12:13], v[124:125], v[74:75]
	s_nop 0
	v_pk_fma_f32 v[74:75], v[28:29], v[122:123], v[74:75]
	s_nop 0
	v_mul_f32_e32 v76, 0x3d372713, v74
	v_mul_f32_e32 v77, 0x3d372713, v75
	v_mul_f32_e32 v76, v74, v76
	v_mul_f32_e32 v77, v75, v77
	v_fma_f32 v76, v74, v76, v74
	v_fma_f32 v77, v75, v77, v75
	v_mul_f32_e32 v76, 0xbfcc422a, v76
	v_mul_f32_e32 v77, 0xbfcc422a, v77
	v_mul_f32_e32 v76, 0x3fb8aa3b, v76
	v_mul_f32_e32 v77, 0x3fb8aa3b, v77
	v_exp_f32_e32 v76, v76
	v_exp_f32_e32 v77, v77
	v_add_f32_e32 v76, 1.0, v76
	v_add_f32_e32 v77, 1.0, v77
	v_rcp_f32_e32 v76, v76
	v_rcp_f32_e32 v77, v77
	s_nop 0
	v_pk_mul_f32 v[74:75], v[74:75], v[76:77]
	s_nop 0
	v_pk_mul_f32 v[96:97], v[96:97], v[74:75]
	v_cvt_pk_bf16_f32 v74, v98, v99
	v_cvt_pk_bf16_f32 v75, v94, v95
	v_cvt_pk_bf16_f32 v76, v106, v107
	v_cvt_pk_bf16_f32 v77, v96, v97
	v_mad_i64_i32 v[94:95], s[22:23], v120, s20, v[154:155]
	global_store_dwordx4 v[94:95], v[74:77], off nt
	v_pk_fma_f32 v[106:107], v[148:149], v[112:113], v[142:143]
	v_lshlrev_b32_e32 v96, 16, v72
	v_lshlrev_b32_e32 v74, 16, v66
	v_and_b32_e32 v75, 0xffff0000, v66
	v_pk_fma_f32 v[90:91], v[30:31], v[74:75], v[90:91]
	v_lshlrev_b32_e32 v76, 16, v70
	v_mul_f32_e32 v66, 0x3d372713, v90
	v_mul_f32_e32 v66, v90, v66
	v_fma_f32 v66, v90, v66, v90
	v_mul_f32_e32 v66, 0xbfcc422a, v66
	v_mul_f32_e32 v66, 0x3fb8aa3b, v66
	v_exp_f32_e32 v66, v66
	v_and_b32_e32 v77, 0xffff0000, v70
	v_pk_fma_f32 v[92:93], v[34:35], v[76:77], v[92:93]
	v_lshlrev_b32_e32 v70, 16, v71
	v_add_f32_e32 v66, 1.0, v66
	v_rcp_f32_e32 v94, v66
	v_mul_f32_e32 v66, 0x3d372713, v91
	v_mul_f32_e32 v66, v91, v66
	v_fma_f32 v66, v91, v66, v91
	v_mul_f32_e32 v66, 0xbfcc422a, v66
	v_mul_f32_e32 v66, 0x3fb8aa3b, v66
	v_exp_f32_e32 v66, v66
	v_and_b32_e32 v71, 0xffff0000, v71
	v_pk_fma_f32 v[86:87], v[36:37], v[70:71], v[86:87]
	v_and_b32_e32 v97, 0xffff0000, v72
	v_add_f32_e32 v66, 1.0, v66
	v_rcp_f32_e32 v95, v66
	v_pk_fma_f32 v[106:107], v[22:23], v[104:105], v[106:107]
	v_lshlrev_b32_e32 v72, 16, v73
	v_pk_fma_f32 v[106:107], v[38:39], v[96:97], v[106:107]
	v_pk_mul_f32 v[90:91], v[90:91], v[94:95]
	v_and_b32_e32 v73, 0xffff0000, v73
	v_pk_mul_f32 v[90:91], v[92:93], v[90:91]
	v_lshlrev_b32_e32 v92, 16, v67
	v_and_b32_e32 v93, 0xffff0000, v67
	v_pk_fma_f32 v[66:67], v[8:9], v[108:109], v[48:49]
	v_pk_fma_f32 v[88:89], v[40:41], v[72:73], v[88:89]
	v_pk_fma_f32 v[66:67], v[16:17], v[100:101], v[66:67]
	v_pk_fma_f32 v[82:83], v[14:15], v[74:75], v[82:83]
	v_pk_fma_f32 v[66:67], v[32:33], v[92:93], v[66:67]
	v_pk_fma_f32 v[84:85], v[18:19], v[76:77], v[84:85]
	v_mul_f32_e32 v94, 0x3d372713, v66
	v_mul_f32_e32 v95, 0x3d372713, v67
	v_mul_f32_e32 v94, v66, v94
	v_mul_f32_e32 v95, v67, v95
	v_fma_f32 v94, v66, v94, v66
	v_fma_f32 v95, v67, v95, v67
	v_mul_f32_e32 v94, 0xbfcc422a, v94
	v_mul_f32_e32 v95, 0xbfcc422a, v95
	v_mul_f32_e32 v94, 0x3fb8aa3b, v94
	v_mul_f32_e32 v95, 0x3fb8aa3b, v95
	v_exp_f32_e32 v94, v94
	v_exp_f32_e32 v95, v95
	v_pk_fma_f32 v[78:79], v[20:21], v[70:71], v[78:79]
	v_pk_fma_f32 v[80:81], v[24:25], v[72:73], v[80:81]
	v_add_f32_e32 v94, 1.0, v94
	v_add_f32_e32 v95, 1.0, v95
	v_rcp_f32_e32 v94, v94
	v_rcp_f32_e32 v95, v95
	v_pk_fma_f32 v[74:75], v[6:7], v[74:75], v[46:47]
	v_pk_mul_f32 v[66:67], v[66:67], v[94:95]
	s_nop 0
	v_pk_mul_f32 v[86:87], v[86:87], v[66:67]
	v_pk_fma_f32 v[66:67], v[2:3], v[110:111], v[42:43]
	v_lshlrev_b32_e32 v94, 16, v68
	v_and_b32_e32 v95, 0xffff0000, v68
	v_pk_fma_f32 v[66:67], v[10:11], v[102:103], v[66:67]
	s_nop 0
	v_pk_fma_f32 v[66:67], v[26:27], v[94:95], v[66:67]
	s_nop 0
	v_mul_f32_e32 v68, 0x3d372713, v66
	v_mul_f32_e32 v68, v66, v68
	v_fma_f32 v68, v66, v68, v66
	v_mul_f32_e32 v68, 0xbfcc422a, v68
	v_mul_f32_e32 v68, 0x3fb8aa3b, v68
	v_exp_f32_e32 v68, v68
	s_nop 0
	v_add_f32_e32 v68, 1.0, v68
	v_rcp_f32_e32 v98, v68
	v_mul_f32_e32 v68, 0x3d372713, v67
	v_mul_f32_e32 v68, v67, v68
	v_fma_f32 v68, v67, v68, v67
	v_mul_f32_e32 v68, 0xbfcc422a, v68
	v_mul_f32_e32 v68, 0x3fb8aa3b, v68
	v_exp_f32_e32 v68, v68
	s_nop 0
	v_add_f32_e32 v68, 1.0, v68
	v_rcp_f32_e32 v99, v68
	s_nop 0
	v_pk_mul_f32 v[66:67], v[66:67], v[98:99]
	s_nop 0
	v_pk_mul_f32 v[98:99], v[106:107], v[66:67]
	v_pk_fma_f32 v[66:67], v[4:5], v[124:125], v[44:45]
	v_lshlrev_b32_e32 v106, 16, v69
	v_and_b32_e32 v107, 0xffff0000, v69
	v_pk_fma_f32 v[66:67], v[12:13], v[122:123], v[66:67]
	s_nop 0
	v_pk_fma_f32 v[66:67], v[28:29], v[106:107], v[66:67]
	s_nop 0
	v_mul_f32_e32 v68, 0x3d372713, v66
	v_mul_f32_e32 v69, 0x3d372713, v67
	v_mul_f32_e32 v68, v66, v68
	v_mul_f32_e32 v69, v67, v69
	v_fma_f32 v68, v66, v68, v66
	v_fma_f32 v69, v67, v69, v67
	v_mul_f32_e32 v68, 0xbfcc422a, v68
	v_mul_f32_e32 v69, 0xbfcc422a, v69
	v_mul_f32_e32 v68, 0x3fb8aa3b, v68
	v_mul_f32_e32 v69, 0x3fb8aa3b, v69
	v_exp_f32_e32 v68, v68
	v_exp_f32_e32 v69, v69
	v_add_f32_e32 v68, 1.0, v68
	v_add_f32_e32 v69, 1.0, v69
	v_rcp_f32_e32 v68, v68
	v_rcp_f32_e32 v69, v69
	s_nop 0
	v_pk_mul_f32 v[66:67], v[66:67], v[68:69]
	s_nop 0
	v_pk_mul_f32 v[88:89], v[88:89], v[66:67]
	v_cvt_pk_bf16_f32 v66, v90, v91
	v_cvt_pk_bf16_f32 v67, v86, v87
	v_cvt_pk_bf16_f32 v68, v98, v99
	v_cvt_pk_bf16_f32 v69, v88, v89
	v_mad_i64_i32 v[86:87], s[22:23], v119, s20, v[154:155]
	global_store_dwordx4 v[86:87], v[66:69], off nt
	v_pk_fma_f32 v[98:99], v[148:149], v[104:105], v[142:143]
	v_lshlrev_b32_e32 v88, 16, v64
	v_lshlrev_b32_e32 v66, 16, v58
	v_and_b32_e32 v67, 0xffff0000, v58
	v_pk_fma_f32 v[82:83], v[30:31], v[66:67], v[82:83]
	v_lshlrev_b32_e32 v68, 16, v62
	v_mul_f32_e32 v58, 0x3d372713, v82
	v_mul_f32_e32 v58, v82, v58
	v_fma_f32 v58, v82, v58, v82
	v_mul_f32_e32 v58, 0xbfcc422a, v58
	v_mul_f32_e32 v58, 0x3fb8aa3b, v58
	v_exp_f32_e32 v58, v58
	v_and_b32_e32 v69, 0xffff0000, v62
	v_pk_fma_f32 v[84:85], v[34:35], v[68:69], v[84:85]
	v_lshlrev_b32_e32 v62, 16, v63
	v_add_f32_e32 v58, 1.0, v58
	v_rcp_f32_e32 v86, v58
	v_mul_f32_e32 v58, 0x3d372713, v83
	v_mul_f32_e32 v58, v83, v58
	v_fma_f32 v58, v83, v58, v83
	v_mul_f32_e32 v58, 0xbfcc422a, v58
	v_mul_f32_e32 v58, 0x3fb8aa3b, v58
	v_exp_f32_e32 v58, v58
	v_and_b32_e32 v63, 0xffff0000, v63
	v_pk_fma_f32 v[78:79], v[36:37], v[62:63], v[78:79]
	v_and_b32_e32 v89, 0xffff0000, v64
	v_add_f32_e32 v58, 1.0, v58
	v_rcp_f32_e32 v87, v58
	v_pk_fma_f32 v[98:99], v[22:23], v[96:97], v[98:99]
	v_lshlrev_b32_e32 v64, 16, v65
	v_pk_fma_f32 v[98:99], v[38:39], v[88:89], v[98:99]
	v_pk_mul_f32 v[82:83], v[82:83], v[86:87]
	v_and_b32_e32 v65, 0xffff0000, v65
	v_pk_mul_f32 v[82:83], v[84:85], v[82:83]
	v_lshlrev_b32_e32 v84, 16, v59
	v_and_b32_e32 v85, 0xffff0000, v59
	v_pk_fma_f32 v[58:59], v[8:9], v[100:101], v[48:49]
	v_pk_fma_f32 v[80:81], v[40:41], v[64:65], v[80:81]
	v_pk_fma_f32 v[58:59], v[16:17], v[92:93], v[58:59]
	v_pk_fma_f32 v[66:67], v[14:15], v[66:67], v[74:75]
	v_pk_fma_f32 v[58:59], v[32:33], v[84:85], v[58:59]
	v_pk_fma_f32 v[74:75], v[138:139], v[76:77], v[136:137]
	v_mul_f32_e32 v86, 0x3d372713, v58
	v_mul_f32_e32 v87, 0x3d372713, v59
	v_mul_f32_e32 v86, v58, v86
	v_mul_f32_e32 v87, v59, v87
	v_fma_f32 v86, v58, v86, v58
	v_fma_f32 v87, v59, v87, v59
	v_mul_f32_e32 v86, 0xbfcc422a, v86
	v_mul_f32_e32 v87, 0xbfcc422a, v87
	v_mul_f32_e32 v86, 0x3fb8aa3b, v86
	v_mul_f32_e32 v87, 0x3fb8aa3b, v87
	v_exp_f32_e32 v86, v86
	v_exp_f32_e32 v87, v87
	v_pk_fma_f32 v[68:69], v[18:19], v[68:69], v[74:75]
	v_add_f32_e32 v86, 1.0, v86
	v_add_f32_e32 v87, 1.0, v87
	v_rcp_f32_e32 v86, v86
	v_rcp_f32_e32 v87, v87
	s_nop 0
	v_pk_mul_f32 v[58:59], v[58:59], v[86:87]
	s_nop 0
	v_pk_mul_f32 v[78:79], v[78:79], v[58:59]
	v_pk_fma_f32 v[58:59], v[2:3], v[102:103], v[42:43]
	v_lshlrev_b32_e32 v86, 16, v60
	v_and_b32_e32 v87, 0xffff0000, v60
	v_pk_fma_f32 v[58:59], v[10:11], v[94:95], v[58:59]
	s_nop 0
	v_pk_fma_f32 v[58:59], v[26:27], v[86:87], v[58:59]
	s_nop 0
	v_mul_f32_e32 v60, 0x3d372713, v58
	v_mul_f32_e32 v60, v58, v60
	v_fma_f32 v60, v58, v60, v58
	v_mul_f32_e32 v60, 0xbfcc422a, v60
	v_mul_f32_e32 v60, 0x3fb8aa3b, v60
	v_exp_f32_e32 v60, v60
	s_nop 0
	v_add_f32_e32 v60, 1.0, v60
	v_rcp_f32_e32 v90, v60
	v_mul_f32_e32 v60, 0x3d372713, v59
	v_mul_f32_e32 v60, v59, v60
	v_fma_f32 v60, v59, v60, v59
	v_mul_f32_e32 v60, 0xbfcc422a, v60
	v_mul_f32_e32 v60, 0x3fb8aa3b, v60
	v_exp_f32_e32 v60, v60
	s_nop 0
	v_add_f32_e32 v60, 1.0, v60
	v_rcp_f32_e32 v91, v60
	s_nop 0
	v_pk_mul_f32 v[58:59], v[58:59], v[90:91]
	s_nop 0
	v_pk_mul_f32 v[90:91], v[98:99], v[58:59]
	v_pk_fma_f32 v[58:59], v[4:5], v[122:123], v[44:45]
	v_lshlrev_b32_e32 v98, 16, v61
	v_and_b32_e32 v99, 0xffff0000, v61
	v_pk_fma_f32 v[58:59], v[12:13], v[106:107], v[58:59]
	s_nop 0
	v_pk_fma_f32 v[58:59], v[28:29], v[98:99], v[58:59]
	s_nop 0
	v_mul_f32_e32 v60, 0x3d372713, v58
	v_mul_f32_e32 v61, 0x3d372713, v59
	v_mul_f32_e32 v60, v58, v60
	v_mul_f32_e32 v61, v59, v61
	v_fma_f32 v60, v58, v60, v58
	v_fma_f32 v61, v59, v61, v59
	v_mul_f32_e32 v60, 0xbfcc422a, v60
	v_mul_f32_e32 v61, 0xbfcc422a, v61
	v_mul_f32_e32 v60, 0x3fb8aa3b, v60
	v_mul_f32_e32 v61, 0x3fb8aa3b, v61
	v_exp_f32_e32 v60, v60
	v_exp_f32_e32 v61, v61
	v_add_f32_e32 v60, 1.0, v60
	v_add_f32_e32 v61, 1.0, v61
	v_rcp_f32_e32 v60, v60
	v_rcp_f32_e32 v61, v61
	s_nop 0
	v_pk_mul_f32 v[58:59], v[58:59], v[60:61]
	s_nop 0
	v_pk_mul_f32 v[80:81], v[80:81], v[58:59]
	v_cvt_pk_bf16_f32 v58, v82, v83
	v_cvt_pk_bf16_f32 v59, v78, v79
	v_cvt_pk_bf16_f32 v60, v90, v91
	v_cvt_pk_bf16_f32 v61, v80, v81
	v_mad_i64_i32 v[78:79], s[22:23], v118, s20, v[154:155]
	global_store_dwordx4 v[78:79], v[58:61], off nt
	s_nop 1
	v_lshlrev_b32_e32 v58, 16, v50
	v_and_b32_e32 v59, 0xffff0000, v50
	v_pk_fma_f32 v[58:59], v[30:31], v[58:59], v[66:67]
	v_lshlrev_b32_e32 v60, 16, v54
	v_mul_f32_e32 v50, 0x3d372713, v58
	v_mul_f32_e32 v50, v58, v50
	v_fma_f32 v50, v58, v50, v58
	v_mul_f32_e32 v50, 0xbfcc422a, v50
	v_mul_f32_e32 v50, 0x3fb8aa3b, v50
	v_exp_f32_e32 v50, v50
	v_and_b32_e32 v61, 0xffff0000, v54
	v_pk_fma_f32 v[60:61], v[34:35], v[60:61], v[68:69]
	v_lshlrev_b32_e32 v54, 16, v55
	v_add_f32_e32 v50, 1.0, v50
	v_rcp_f32_e32 v66, v50
	v_mul_f32_e32 v50, 0x3d372713, v59
	v_mul_f32_e32 v50, v59, v50
	v_fma_f32 v50, v59, v50, v59
	v_mul_f32_e32 v50, 0xbfcc422a, v50
	v_mul_f32_e32 v50, 0x3fb8aa3b, v50
	v_exp_f32_e32 v50, v50
	v_and_b32_e32 v55, 0xffff0000, v55
	v_add_f32_e32 v50, 1.0, v50
	v_rcp_f32_e32 v67, v50
	v_lshlrev_b32_e32 v50, 16, v51
	v_and_b32_e32 v51, 0xffff0000, v51
	v_pk_mul_f32 v[58:59], v[58:59], v[66:67]
	s_nop 0
	v_pk_mul_f32 v[58:59], v[60:61], v[58:59]
	v_pk_fma_f32 v[60:61], v[8:9], v[92:93], v[48:49]
	v_pk_fma_f32 v[66:67], v[146:147], v[70:71], v[140:141]
	v_pk_fma_f32 v[60:61], v[16:17], v[84:85], v[60:61]
	v_pk_fma_f32 v[62:63], v[20:21], v[62:63], v[66:67]
	v_pk_fma_f32 v[50:51], v[32:33], v[50:51], v[60:61]
	v_pk_fma_f32 v[54:55], v[36:37], v[54:55], v[62:63]
	v_mul_f32_e32 v60, 0x3d372713, v50
	v_mul_f32_e32 v61, 0x3d372713, v51
	v_mul_f32_e32 v60, v50, v60
	v_mul_f32_e32 v61, v51, v61
	v_fma_f32 v60, v50, v60, v50
	v_fma_f32 v61, v51, v61, v51
	v_mul_f32_e32 v60, 0xbfcc422a, v60
	v_mul_f32_e32 v61, 0xbfcc422a, v61
	v_mul_f32_e32 v60, 0x3fb8aa3b, v60
	v_mul_f32_e32 v61, 0x3fb8aa3b, v61
	v_exp_f32_e32 v60, v60
	v_exp_f32_e32 v61, v61
	v_pk_fma_f32 v[62:63], v[2:3], v[94:95], v[42:43]
	v_pk_fma_f32 v[66:67], v[148:149], v[96:97], v[142:143]
	v_add_f32_e32 v60, 1.0, v60
	v_add_f32_e32 v61, 1.0, v61
	v_rcp_f32_e32 v60, v60
	v_rcp_f32_e32 v61, v61
	v_pk_fma_f32 v[62:63], v[10:11], v[86:87], v[62:63]
	v_pk_fma_f32 v[66:67], v[22:23], v[88:89], v[66:67]
	v_pk_mul_f32 v[50:51], v[50:51], v[60:61]
	s_nop 0
	v_pk_mul_f32 v[54:55], v[54:55], v[50:51]
	v_lshlrev_b32_e32 v50, 16, v52
	v_and_b32_e32 v51, 0xffff0000, v52
	v_pk_fma_f32 v[50:51], v[26:27], v[50:51], v[62:63]
	v_lshlrev_b32_e32 v60, 16, v56
	v_mul_f32_e32 v52, 0x3d372713, v50
	v_mul_f32_e32 v52, v50, v52
	v_fma_f32 v52, v50, v52, v50
	v_mul_f32_e32 v52, 0xbfcc422a, v52
	v_mul_f32_e32 v52, 0x3fb8aa3b, v52
	v_exp_f32_e32 v52, v52
	v_and_b32_e32 v61, 0xffff0000, v56
	v_pk_fma_f32 v[60:61], v[38:39], v[60:61], v[66:67]
	v_add_f32_e32 v52, 1.0, v52
	v_rcp_f32_e32 v62, v52
	v_mul_f32_e32 v52, 0x3d372713, v51
	v_mul_f32_e32 v52, v51, v52
	v_fma_f32 v52, v51, v52, v51
	v_mul_f32_e32 v52, 0xbfcc422a, v52
	v_mul_f32_e32 v52, 0x3fb8aa3b, v52
	v_exp_f32_e32 v52, v52
	s_nop 0
	v_add_f32_e32 v52, 1.0, v52
	v_rcp_f32_e32 v63, v52
	v_lshlrev_b32_e32 v52, 16, v57
	v_pk_mul_f32 v[50:51], v[50:51], v[62:63]
	s_nop 0
	v_pk_mul_f32 v[60:61], v[60:61], v[50:51]
	v_lshlrev_b32_e32 v50, 16, v53
	v_and_b32_e32 v51, 0xffff0000, v53
	v_and_b32_e32 v53, 0xffff0000, v57
	v_pk_fma_f32 v[56:57], v[4:5], v[106:107], v[44:45]
	v_pk_fma_f32 v[62:63], v[150:151], v[72:73], v[144:145]
	v_pk_fma_f32 v[56:57], v[12:13], v[98:99], v[56:57]
	v_pk_fma_f32 v[62:63], v[24:25], v[64:65], v[62:63]
	v_pk_fma_f32 v[50:51], v[28:29], v[50:51], v[56:57]
	v_pk_fma_f32 v[52:53], v[40:41], v[52:53], v[62:63]
	v_mul_f32_e32 v56, 0x3d372713, v50
	v_mul_f32_e32 v57, 0x3d372713, v51
	v_mul_f32_e32 v56, v50, v56
	v_mul_f32_e32 v57, v51, v57
	v_fma_f32 v56, v50, v56, v50
	v_fma_f32 v57, v51, v57, v51
	v_mul_f32_e32 v56, 0xbfcc422a, v56
	v_mul_f32_e32 v57, 0xbfcc422a, v57
	v_mul_f32_e32 v56, 0x3fb8aa3b, v56
	v_mul_f32_e32 v57, 0x3fb8aa3b, v57
	v_exp_f32_e32 v56, v56
	v_exp_f32_e32 v57, v57
	v_add_f32_e32 v56, 1.0, v56
	v_add_f32_e32 v57, 1.0, v57
	v_rcp_f32_e32 v56, v56
	v_rcp_f32_e32 v57, v57
	s_nop 0
	v_pk_mul_f32 v[50:51], v[50:51], v[56:57]
	s_nop 0
	v_pk_mul_f32 v[56:57], v[52:53], v[50:51]
	v_cvt_pk_bf16_f32 v50, v58, v59
	v_cvt_pk_bf16_f32 v51, v54, v55
	v_cvt_pk_bf16_f32 v52, v60, v61
	v_cvt_pk_bf16_f32 v53, v56, v57
	v_mad_i64_i32 v[54:55], s[22:23], v117, s20, v[154:155]
	global_store_dwordx4 v[54:55], v[50:53], off nt
	s_andn2_b64 exec, exec, s[0:1]
	s_cbranch_execnz .LBB0_863

.LBB0_997:
	v_mul_f32_e32 v168, v67, v67
	v_mul_f32_e32 v169, v69, v69
	v_fmac_f32_e32 v168, v66, v66
	v_fmac_f32_e32 v169, v68, v68
	v_add_f32_e32 v168, v168, v169
	v_mul_f32_e32 v169, v71, v71
	v_mul_f32_e32 v178, v73, v73
	v_fmac_f32_e32 v169, v70, v70
	v_fmac_f32_e32 v178, v72, v72
	v_add_f32_e32 v169, v169, v178
	v_add_f32_e32 v168, v168, v169
	v_mul_f32_e32 v169, v75, v75
	v_mul_f32_e32 v178, v77, v77
	v_fmac_f32_e32 v169, v74, v74
	v_fmac_f32_e32 v178, v76, v76
	v_add_f32_e32 v169, v169, v178
	v_add_f32_e32 v168, v168, v169
	v_mul_f32_e32 v169, v79, v79
	v_mul_f32_e32 v178, v81, v81
	v_fmac_f32_e32 v169, v78, v78
	v_fmac_f32_e32 v178, v80, v80
	v_add_f32_e32 v169, v169, v178
	v_add_f32_e32 v168, v168, v169
	v_mul_f32_e32 v169, v83, v83
	v_mul_f32_e32 v178, v85, v85
	v_fmac_f32_e32 v169, v82, v82
	v_fmac_f32_e32 v178, v84, v84
	v_add_f32_e32 v169, v169, v178
	v_add_f32_e32 v168, v168, v169
	v_mul_f32_e32 v169, v87, v87
	v_mul_f32_e32 v178, v89, v89
	v_fmac_f32_e32 v169, v86, v86
	v_fmac_f32_e32 v178, v88, v88
	v_add_f32_e32 v169, v169, v178
	v_add_f32_e32 v168, v168, v169
	v_mul_f32_e32 v169, v91, v91
	v_mul_f32_e32 v178, v93, v93
	v_fmac_f32_e32 v169, v90, v90
	v_fmac_f32_e32 v178, v92, v92
	v_add_f32_e32 v169, v169, v178
	v_add_f32_e32 v168, v168, v169
	v_mul_f32_e32 v169, v95, v95
	v_mul_f32_e32 v178, v97, v97
	v_fmac_f32_e32 v169, v94, v94
	v_fmac_f32_e32 v178, v96, v96
	v_add_f32_e32 v169, v169, v178
	v_add_f32_e32 v168, v168, v169
	v_mul_f32_e32 v169, v99, v99
	v_mul_f32_e32 v178, v101, v101
	v_fmac_f32_e32 v169, v98, v98
	v_fmac_f32_e32 v178, v100, v100
	v_add_f32_e32 v169, v169, v178
	v_add_f32_e32 v168, v168, v169
	v_mul_f32_e32 v169, v103, v103
	v_mul_f32_e32 v178, v105, v105
	v_fmac_f32_e32 v169, v102, v102
	v_fmac_f32_e32 v178, v104, v104
	v_add_f32_e32 v169, v169, v178
	v_add_f32_e32 v168, v168, v169
	v_mul_f32_e32 v169, v107, v107
	v_mul_f32_e32 v178, v109, v109
	v_fmac_f32_e32 v169, v106, v106
	v_fmac_f32_e32 v178, v108, v108
	v_add_f32_e32 v169, v169, v178
	v_add_f32_e32 v168, v168, v169
	v_mul_f32_e32 v169, v111, v111
	v_mul_f32_e32 v178, v113, v113
	v_fmac_f32_e32 v169, v110, v110
	v_fmac_f32_e32 v178, v112, v112
	v_add_f32_e32 v169, v169, v178
	v_add_f32_e32 v168, v168, v169
	v_mul_f32_e32 v169, v115, v115
	v_mul_f32_e32 v178, v117, v117
	v_fmac_f32_e32 v169, v114, v114
	v_fmac_f32_e32 v178, v116, v116
	v_add_f32_e32 v169, v169, v178
	v_add_f32_e32 v168, v168, v169
	v_mul_f32_e32 v169, v119, v119
	v_mul_f32_e32 v178, v121, v121
	v_fmac_f32_e32 v169, v118, v118
	v_fmac_f32_e32 v178, v120, v120
	v_add_f32_e32 v169, v169, v178
	v_add_f32_e32 v168, v168, v169
	v_mul_f32_e32 v169, v123, v123
	v_mul_f32_e32 v178, v125, v125
	v_fmac_f32_e32 v169, v122, v122
	v_fmac_f32_e32 v178, v124, v124
	s_waitcnt vmcnt(12)
	v_lshlrev_b32_e32 v184, 16, v160
	v_and_b32_e32 v185, 0xffff0000, v160
	v_lshlrev_b32_e32 v186, 16, v161
	v_and_b32_e32 v187, 0xffff0000, v161
	s_waitcnt vmcnt(9)
	v_lshlrev_b32_e32 v196, 16, v154
	v_and_b32_e32 v197, 0xffff0000, v154
	s_waitcnt vmcnt(8)
	v_lshlrev_b32_e32 v160, 16, v152
	v_and_b32_e32 v161, 0xffff0000, v152
	v_lshlrev_b32_e32 v200, 16, v153
	v_and_b32_e32 v201, 0xffff0000, v153
	s_waitcnt vmcnt(7)
	v_lshlrev_b32_e32 v152, 16, v150
	v_and_b32_e32 v153, 0xffff0000, v150
	v_mul_f32_e32 v150, v127, v127
	v_mul_f32_e32 v154, v129, v129
	v_add_f32_e32 v169, v169, v178
	v_fmac_f32_e32 v150, v126, v126
	v_fmac_f32_e32 v154, v128, v128
	v_add_f32_e32 v202, v168, v169
	v_add_f32_e32 v150, v150, v154
	v_add_f32_e32 v150, v202, v150
	ds_bpermute_b32 v154, v170, v150
	s_waitcnt vmcnt(6)
	v_lshlrev_b32_e32 v204, 16, v148
	v_and_b32_e32 v205, 0xffff0000, v148
	v_lshlrev_b32_e32 v180, 16, v162
	v_and_b32_e32 v181, 0xffff0000, v162
	s_waitcnt lgkmcnt(0)
	v_add_f32_e32 v148, v150, v154
	ds_bpermute_b32 v150, v171, v148
	v_lshlrev_b32_e32 v182, 16, v163
	v_and_b32_e32 v183, 0xffff0000, v163
	s_waitcnt vmcnt(5)
	v_lshlrev_b32_e32 v162, 16, v146
	v_and_b32_e32 v163, 0xffff0000, v146
	s_waitcnt lgkmcnt(0)
	v_add_f32_e32 v146, v148, v150
	ds_bpermute_b32 v148, v172, v146
	v_lshlrev_b32_e32 v192, 16, v156
	v_and_b32_e32 v193, 0xffff0000, v156
	v_lshlrev_b32_e32 v194, 16, v157
	v_and_b32_e32 v195, 0xffff0000, v157
	s_waitcnt vmcnt(4)
	v_lshlrev_b32_e32 v156, 16, v144
	v_and_b32_e32 v157, 0xffff0000, v144
	s_waitcnt lgkmcnt(0)
	v_add_f32_e32 v144, v146, v148
	ds_bpermute_b32 v146, v173, v144
	v_lshlrev_b32_e32 v188, 16, v158
	v_and_b32_e32 v189, 0xffff0000, v158
	v_lshlrev_b32_e32 v190, 16, v159
	v_and_b32_e32 v191, 0xffff0000, v159
	s_waitcnt lgkmcnt(0)
	v_add_f32_e32 v144, v144, v146
	v_lshlrev_b32_e32 v158, 16, v145
	v_and_b32_e32 v159, 0xffff0000, v145
	ds_bpermute_b32 v145, v175, v144
	v_lshlrev_b32_e32 v198, 16, v155
	v_and_b32_e32 v199, 0xffff0000, v155
	v_lshlrev_b32_e32 v206, 16, v149
	v_and_b32_e32 v207, 0xffff0000, v149
	s_waitcnt lgkmcnt(0)
	v_add_f32_e32 v144, v144, v145
	ds_bpermute_b32 v145, v176, v144
	v_lshlrev_b32_e32 v208, 16, v147
	v_and_b32_e32 v209, 0xffff0000, v147
	s_waitcnt vmcnt(3)
	v_lshlrev_b32_e32 v148, 16, v142
	v_and_b32_e32 v149, 0xffff0000, v142
	v_lshlrev_b32_e32 v154, 16, v143
	v_and_b32_e32 v155, 0xffff0000, v143
	s_waitcnt vmcnt(2)
	v_lshlrev_b32_e32 v142, 16, v140
	v_and_b32_e32 v143, 0xffff0000, v140
	v_lshlrev_b32_e32 v146, 16, v141
	v_and_b32_e32 v147, 0xffff0000, v141
	s_waitcnt vmcnt(1)
	v_lshlrev_b32_e32 v140, 16, v138
	v_and_b32_e32 v141, 0xffff0000, v138
	s_waitcnt lgkmcnt(0)
	v_add_f32_e32 v138, v144, v145
	v_fmamk_f32 v138, v138, 0x39800000, v174
	v_mul_f32_e32 v144, 0x4f800000, v138
	v_cmp_gt_f32_e32 vcc, s7, v138
	v_lshlrev_b32_e32 v202, 16, v151
	v_and_b32_e32 v203, 0xffff0000, v151
	v_cndmask_b32_e32 v150, v138, v144, vcc
	v_sqrt_f32_e32 v151, v150
	v_lshlrev_b32_e32 v144, 16, v139
	v_and_b32_e32 v145, 0xffff0000, v139
	v_lshlrev_b32_e32 v168, 16, v166
	v_add_u32_e32 v139, -1, v151
	v_fma_f32 v210, -v139, v151, v150
	v_cmp_ge_f32_e64 s[0:1], 0, v210
	v_add_u32_e32 v210, 1, v151
	v_and_b32_e32 v169, 0xffff0000, v166
	v_cndmask_b32_e64 v139, v151, v139, s[0:1]
	v_fma_f32 v151, -v210, v151, v150
	v_cmp_lt_f32_e64 s[0:1], 0, v151
	v_lshlrev_b32_e32 v166, 16, v167
	v_and_b32_e32 v167, 0xffff0000, v167
	v_cndmask_b32_e64 v139, v139, v210, s[0:1]
	v_mul_f32_e32 v151, 0x37800000, v139
	v_cndmask_b32_e32 v139, v139, v151, vcc
	v_cmp_class_f32_e32 vcc, v150, v177
	v_lshlrev_b32_e32 v178, 16, v164
	v_and_b32_e32 v179, 0xffff0000, v164
	v_cndmask_b32_e32 v150, v139, v150, vcc
	v_div_scale_f32 v151, s[0:1], v150, v150, 1.0
	v_rcp_f32_e32 v210, v151
	v_lshlrev_b32_e32 v164, 16, v165
	v_and_b32_e32 v165, 0xffff0000, v165
	s_add_i32 s4, s4, s6
	v_fma_f32 v211, -v151, v210, 1.0
	v_fmac_f32_e32 v210, v211, v210
	v_div_scale_f32 v211, vcc, 1.0, v150, 1.0
	v_mul_f32_e32 v212, v211, v210
	v_fma_f32 v213, -v151, v212, v211
	v_fmac_f32_e32 v212, v213, v210
	v_fma_f32 v151, -v151, v212, v211
	v_div_fmas_f32 v151, v151, v210, v212
	v_div_fixup_f32 v150, v151, v150, 1.0
	v_pk_mul_f32 v[66:67], v[66:67], v[150:151] op_sel_hi:[1,0]
	v_pk_mul_f32 v[68:69], v[68:69], v[150:151] op_sel_hi:[1,0]
	v_pk_fma_f32 v[66:67], v[2:3], v[66:67], v[168:169]
	v_pk_fma_f32 v[68:69], v[4:5], v[68:69], v[166:167]
	v_lshl_add_u64 v[166:167], s[10:11], 0, v[130:131]
	global_store_dwordx4 v[166:167], v[66:69], off nt
	s_add_i32 s23, s23, s24
	s_waitcnt vmcnt(1)
	v_lshlrev_b32_e32 v138, 16, v136
	v_pk_mul_f32 v[66:67], v[70:71], v[150:151] op_sel_hi:[1,0]
	v_pk_mul_f32 v[68:69], v[72:73], v[150:151] op_sel_hi:[1,0]
	v_pk_fma_f32 v[66:67], v[6:7], v[66:67], v[178:179]
	v_pk_fma_f32 v[68:69], v[8:9], v[68:69], v[164:165]
	global_store_dwordx4 v[166:167], v[66:69], off offset:1024 nt
	v_add_co_u32_e32 v70, vcc, s5, v166
	s_nop 0
	v_pk_mul_f32 v[66:67], v[74:75], v[150:151] op_sel_hi:[1,0]
	v_pk_mul_f32 v[68:69], v[76:77], v[150:151] op_sel_hi:[1,0]
	v_pk_fma_f32 v[66:67], v[10:11], v[66:67], v[180:181]
	v_pk_fma_f32 v[68:69], v[12:13], v[68:69], v[182:183]
	global_store_dwordx4 v[166:167], v[66:69], off offset:2048 nt
	v_addc_co_u32_e32 v71, vcc, 0, v167, vcc
	s_nop 0
	v_pk_mul_f32 v[66:67], v[78:79], v[150:151] op_sel_hi:[1,0]
	v_pk_mul_f32 v[68:69], v[80:81], v[150:151] op_sel_hi:[1,0]
	v_pk_fma_f32 v[66:67], v[14:15], v[66:67], v[184:185]
	v_pk_fma_f32 v[68:69], v[16:17], v[68:69], v[186:187]
	global_store_dwordx4 v[166:167], v[66:69], off offset:3072 nt
	v_add_co_u32_e32 v72, vcc, s20, v166
	s_nop 0
	v_pk_mul_f32 v[66:67], v[82:83], v[150:151] op_sel_hi:[1,0]
	v_pk_mul_f32 v[68:69], v[84:85], v[150:151] op_sel_hi:[1,0]
	v_pk_fma_f32 v[66:67], v[18:19], v[66:67], v[188:189]
	v_pk_fma_f32 v[68:69], v[20:21], v[68:69], v[190:191]
	v_addc_co_u32_e32 v73, vcc, 0, v167, vcc
	global_store_dwordx4 v[72:73], v[66:69], off offset:-4096 nt
	v_and_b32_e32 v139, 0xffff0000, v136
	v_lshlrev_b32_e32 v136, 16, v137
	v_pk_mul_f32 v[66:67], v[86:87], v[150:151] op_sel_hi:[1,0]
	v_pk_mul_f32 v[68:69], v[88:89], v[150:151] op_sel_hi:[1,0]
	v_pk_fma_f32 v[66:67], v[22:23], v[66:67], v[192:193]
	v_pk_fma_f32 v[68:69], v[24:25], v[68:69], v[194:195]
	global_store_dwordx4 v[70:71], v[66:69], off offset:1024 nt
	v_and_b32_e32 v137, 0xffff0000, v137
	v_lshl_add_u64 v[132:133], v[132:133], 0, s[8:9]
	v_pk_mul_f32 v[66:67], v[90:91], v[150:151] op_sel_hi:[1,0]
	v_pk_mul_f32 v[68:69], v[92:93], v[150:151] op_sel_hi:[1,0]
	v_pk_fma_f32 v[66:67], v[66:67], v[26:27], v[196:197]
	v_pk_fma_f32 v[68:69], v[68:69], v[28:29], v[198:199]
	global_store_dwordx4 v[70:71], v[66:69], off offset:2048 nt
	s_nop 1
	v_pk_mul_f32 v[66:67], v[94:95], v[150:151] op_sel_hi:[1,0]
	v_pk_mul_f32 v[68:69], v[96:97], v[150:151] op_sel_hi:[1,0]
	v_pk_fma_f32 v[66:67], v[66:67], v[30:31], v[160:161]
	v_pk_fma_f32 v[68:69], v[68:69], v[32:33], v[200:201]
	global_store_dwordx4 v[70:71], v[66:69], off offset:3072 nt
	v_add_co_u32_e32 v70, vcc, s25, v166
	s_nop 0
	v_pk_mul_f32 v[66:67], v[98:99], v[150:151] op_sel_hi:[1,0]
	v_pk_mul_f32 v[68:69], v[100:101], v[150:151] op_sel_hi:[1,0]
	v_pk_fma_f32 v[66:67], v[66:67], v[34:35], v[152:153]
	v_pk_fma_f32 v[68:69], v[68:69], v[36:37], v[202:203]
	global_store_dwordx4 v[72:73], v[66:69], off nt
	v_addc_co_u32_e32 v71, vcc, 0, v167, vcc
	s_nop 0
	v_pk_mul_f32 v[66:67], v[102:103], v[150:151] op_sel_hi:[1,0]
	v_pk_mul_f32 v[68:69], v[104:105], v[150:151] op_sel_hi:[1,0]
	v_pk_fma_f32 v[66:67], v[66:67], v[38:39], v[204:205]
	v_pk_fma_f32 v[68:69], v[68:69], v[40:41], v[206:207]
	global_store_dwordx4 v[72:73], v[66:69], off offset:1024 nt
	s_nop 1
	v_pk_mul_f32 v[66:67], v[106:107], v[150:151] op_sel_hi:[1,0]
	v_pk_mul_f32 v[68:69], v[108:109], v[150:151] op_sel_hi:[1,0]
	v_pk_fma_f32 v[66:67], v[66:67], v[42:43], v[162:163]
	v_pk_fma_f32 v[68:69], v[68:69], v[44:45], v[208:209]
	global_store_dwordx4 v[72:73], v[66:69], off offset:2048 nt
	s_nop 1
	v_pk_mul_f32 v[66:67], v[110:111], v[150:151] op_sel_hi:[1,0]
	v_pk_mul_f32 v[68:69], v[112:113], v[150:151] op_sel_hi:[1,0]
	v_pk_fma_f32 v[66:67], v[66:67], v[46:47], v[156:157]
	v_pk_fma_f32 v[68:69], v[68:69], v[48:49], v[158:159]
	global_store_dwordx4 v[72:73], v[66:69], off offset:3072 nt
	s_nop 1
	v_pk_mul_f32 v[66:67], v[114:115], v[150:151] op_sel_hi:[1,0]
	v_pk_mul_f32 v[68:69], v[116:117], v[150:151] op_sel_hi:[1,0]
	v_pk_fma_f32 v[66:67], v[66:67], v[50:51], v[148:149]
	v_pk_fma_f32 v[68:69], v[68:69], v[52:53], v[154:155]
	global_store_dwordx4 v[70:71], v[66:69], off nt
	s_nop 1
	v_pk_mul_f32 v[66:67], v[118:119], v[150:151] op_sel_hi:[1,0]
	v_pk_mul_f32 v[68:69], v[120:121], v[150:151] op_sel_hi:[1,0]
	v_pk_fma_f32 v[66:67], v[66:67], v[54:55], v[142:143]
	v_pk_fma_f32 v[68:69], v[68:69], v[56:57], v[146:147]
	global_store_dwordx4 v[70:71], v[66:69], off offset:1024 nt
	s_nop 1
	v_pk_mul_f32 v[66:67], v[122:123], v[150:151] op_sel_hi:[1,0]
	v_pk_mul_f32 v[68:69], v[124:125], v[150:151] op_sel_hi:[1,0]
	v_pk_fma_f32 v[66:67], v[66:67], v[58:59], v[140:141]
	v_pk_fma_f32 v[68:69], v[68:69], v[60:61], v[144:145]
	global_store_dwordx4 v[70:71], v[66:69], off offset:2048 nt
	v_lshl_add_u64 v[70:71], s[10:11], 0, v[0:1]
	s_add_u32 s10, s10, s12
	v_pk_mul_f32 v[66:67], v[126:127], v[150:151] op_sel_hi:[1,0]
	v_pk_mul_f32 v[68:69], v[128:129], v[150:151] op_sel_hi:[1,0]
	s_addc_u32 s11, s11, s13
	v_pk_fma_f32 v[68:69], v[68:69], v[64:65], v[136:137]
	v_pk_fma_f32 v[66:67], v[66:67], v[62:63], v[138:139]
	s_cmpk_lt_i32 s4, 0x2400
	global_store_dwordx4 v[70:71], v[66:69], off nt
	s_cbranch_scc0 .LBB0_1062
